# v76: ret chunk scan first vmcnt(0) relaxed to vmcnt(32) on top of gate10 phase rewrite
# speedup vs baseline: 1.0284x; 1.0090x over previous
; #define PG8_STAGE(bufoff, gbase, voff) do { _Pragma("unroll") for (int _i = 0; _i < 2; ++_i) \
;         __builtin_amdgcn_global_load_lds((const unsigned*)((const char*)(gbase) + (voff)[_i]), (LAS unsigned*)(lds + (bufoff) + ldsw + _i * 8192), 16, 0, 0); } while (0)
; #define PG8_LDA(dst, b, h) do { _Pragma("unroll") for (int m = 0; m < 4; ++m) _Pragma("unroll") for (int k = 0; k < 2; ++k) dst[m][k] = *(const LAS bf16x8*)(lds + PG8_SA(b, h) + aoff + m * 2048 + k * 1024); } while (0)
; #define PG8_LDB(dst, b, h) do { _Pragma("unroll") for (int n = 0; n < 2; ++n) _Pragma("unroll") for (int k = 0; k < 2; ++k) dst[n][k] = *(const LAS bf16x8*)(lds + PG8_SB(b, h) + boff + n * 2048 + k * 1024); } while (0)
; #define PG8_MMA(ai, bj, At, Bt) do { __builtin_amdgcn_s_setprio(1); _Pragma("unroll") for (int m = 0; m < 4; ++m) _Pragma("unroll") for (int n = 0; n < 2; ++n) _Pragma("unroll") for (int k = 0; k < 2; ++k) \
;         acc[ai][bj][m][n] = __builtin_amdgcn_mfma_f32_16x16x32_bf16(Bt[n][k], At[m][k], acc[ai][bj][m][n], 0, 0, 0); __builtin_amdgcn_s_setprio(0); } while (0)
; #define PG8_WAIT_L(n) asm volatile("s_waitcnt lgkmcnt(" #n ")" ::: "memory")
; #define PG8_BAR __builtin_amdgcn_s_barrier()
; #define PG8_SCHED __builtin_amdgcn_sched_barrier(0)
; template <class Epi, class Sched>
; DI void gemm_phase(LAS unsigned char* lds, const Gemm g, const Sched& S, const Epi& E) {
;     ...
;             PG8_LDB(B0, 0, 0); PG8_SCHED; PG8_LDA(At, 0, 0); PG8_STAGE(PG8_SA(1, 1), a1 + hstep, voffA);
;             PG8_WAIT_L(8); PG8_BAR; PG8_WAIT_L(0); PG8_MMA(0, 0, At, B0); PG8_BAR; PG8_SCHED;
;             PG8_LDB(B1, 0, 1); PG8_STAGE(PG8_SB(0, 0), b2, voffB);
;             PG8_BAR; PG8_WAIT_L(0); PG8_MMA(0, 1, At, B1); PG8_BAR;
;             PG8_LDA(At, 0, 1); PG8_STAGE(PG8_SA(0, 0), a2, voffA);
;             PG8_BAR; PG8_WAIT_L(0); PG8_MMA(1, 0, At, B0); PG8_BAR; PG8_SCHED;
.LBB0_1007:
	ds_read_b128 v[140:143], v147
	ds_read_b128 v[154:157], v147 offset:1024
	ds_read_b128 v[158:161], v147 offset:2048
	ds_read_b128 v[164:167], v147 offset:3072
	s_add_u32 s24, s22, 0xfffc0080
	s_addc_u32 s25, s23, -1
	s_cmp_eq_u32 s66, 12
	s_cselect_b32 s27, s47, s25
	s_cselect_b32 s26, s53, s24
	s_cselect_b32 s25, s54, s59
	s_cselect_b32 s24, s55, s58
	s_mov_b32 m0, s36
	v_lshl_add_u64 v[150:151], s[22:23], 0, v[136:137]
	ds_read_b128 v[168:171], v148
	ds_read_b128 v[172:175], v148 offset:1024
	ds_read_b128 v[176:179], v148 offset:2048
	ds_read_b128 v[180:183], v148 offset:3072
	ds_read_b128 v[184:187], v148 offset:4096
	ds_read_b128 v[188:191], v148 offset:5120
	ds_read_b128 v[192:195], v148 offset:6144
	ds_read_b128 v[198:201], v148 offset:7168
	global_load_lds_dwordx4 v[150:151], off
	v_lshl_add_u64 v[150:151], s[22:23], 0, v[138:139]
	s_mov_b32 m0, s37
	s_nop 0
	global_load_lds_dwordx4 v[150:151], off
	s_waitcnt lgkmcnt(8)
	s_barrier
	s_waitcnt lgkmcnt(0)
	s_setprio 1
	s_waitcnt lgkmcnt(0)
	v_mfma_f32_16x16x32_bf16 v[126:129], v[140:143], v[168:171], v[126:129]
	v_mfma_f32_16x16x32_bf16 v[122:125], v[158:161], v[168:171], v[122:125]
	v_mfma_f32_16x16x32_bf16 v[114:117], v[140:143], v[176:179], v[114:117]
	v_mfma_f32_16x16x32_bf16 v[106:109], v[158:161], v[176:179], v[106:109]
	v_mfma_f32_16x16x32_bf16 v[98:101], v[140:143], v[184:187], v[98:101]
	v_mfma_f32_16x16x32_bf16 v[90:93], v[158:161], v[184:187], v[90:93]
	v_mfma_f32_16x16x32_bf16 v[82:85], v[140:143], v[192:195], v[82:85]
	v_mfma_f32_16x16x32_bf16 v[74:77], v[158:161], v[192:195], v[74:77]
	v_mfma_f32_16x16x32_bf16 v[126:129], v[154:157], v[172:175], v[126:129]
	v_mfma_f32_16x16x32_bf16 v[122:125], v[164:167], v[172:175], v[122:125]
	v_mfma_f32_16x16x32_bf16 v[114:117], v[154:157], v[180:183], v[114:117]
	v_mfma_f32_16x16x32_bf16 v[106:109], v[164:167], v[180:183], v[106:109]
	v_mfma_f32_16x16x32_bf16 v[98:101], v[154:157], v[188:191], v[98:101]
	v_mfma_f32_16x16x32_bf16 v[90:93], v[164:167], v[188:191], v[90:93]
	v_mfma_f32_16x16x32_bf16 v[82:85], v[154:157], v[198:201], v[82:85]
	v_mfma_f32_16x16x32_bf16 v[74:77], v[164:167], v[198:201], v[74:77]
	s_setprio 0
	s_barrier
	s_mov_b32 m0, s38
	v_lshl_add_u64 v[150:151], s[24:25], 0, v[132:133]
	ds_read_b128 v[202:205], v149
	ds_read_b128 v[206:209], v149 offset:1024
	ds_read_b128 v[210:213], v149 offset:2048
	ds_read_b128 v[214:217], v149 offset:3072
	global_load_lds_dwordx4 v[150:151], off
	v_lshl_add_u64 v[218:219], s[24:25], 0, v[130:131]
	s_mov_b32 m0, s39
	s_nop 0
	global_load_lds_dwordx4 v[218:219], off
	s_barrier
	s_waitcnt lgkmcnt(0)
	s_setprio 1
	s_waitcnt lgkmcnt(0)
	v_mfma_f32_16x16x32_bf16 v[118:121], v[202:205], v[168:171], v[118:121]
	v_mfma_f32_16x16x32_bf16 v[110:113], v[210:213], v[168:171], v[110:113]
	v_mfma_f32_16x16x32_bf16 v[102:105], v[202:205], v[176:179], v[102:105]
	v_mfma_f32_16x16x32_bf16 v[94:97], v[210:213], v[176:179], v[94:97]
	v_mfma_f32_16x16x32_bf16 v[86:89], v[202:205], v[184:187], v[86:89]
	v_mfma_f32_16x16x32_bf16 v[78:81], v[210:213], v[184:187], v[78:81]
	v_mfma_f32_16x16x32_bf16 v[70:73], v[202:205], v[192:195], v[70:73]
	v_mfma_f32_16x16x32_bf16 v[66:69], v[210:213], v[192:195], v[66:69]
	v_mfma_f32_16x16x32_bf16 v[118:121], v[206:209], v[172:175], v[118:121]
	v_mfma_f32_16x16x32_bf16 v[110:113], v[214:217], v[172:175], v[110:113]
	v_mfma_f32_16x16x32_bf16 v[102:105], v[206:209], v[180:183], v[102:105]
	v_mfma_f32_16x16x32_bf16 v[94:97], v[214:217], v[180:183], v[94:97]
	v_mfma_f32_16x16x32_bf16 v[86:89], v[206:209], v[188:191], v[86:89]
	v_mfma_f32_16x16x32_bf16 v[78:81], v[214:217], v[188:191], v[78:81]
	v_mfma_f32_16x16x32_bf16 v[70:73], v[206:209], v[198:201], v[70:73]
	v_mfma_f32_16x16x32_bf16 v[66:69], v[214:217], v[198:201], v[66:69]
	s_setprio 0
	s_mov_b32 m0, s13
	v_lshl_add_u64 v[220:221], s[26:27], 0, v[132:133]
	s_barrier
	ds_read_b128 v[168:171], v148 offset:16384
	ds_read_b128 v[172:175], v148 offset:17408
	ds_read_b128 v[176:179], v148 offset:18432
	ds_read_b128 v[180:183], v148 offset:19456
	ds_read_b128 v[184:187], v148 offset:20480
	ds_read_b128 v[188:191], v148 offset:21504
	ds_read_b128 v[192:195], v148 offset:22528
	ds_read_b128 v[198:201], v148 offset:23552
	global_load_lds_dwordx4 v[220:221], off
	v_lshl_add_u64 v[222:223], s[26:27], 0, v[130:131]
	s_mov_b32 m0, s28
	s_nop 0
	global_load_lds_dwordx4 v[222:223], off
	s_barrier
	s_waitcnt lgkmcnt(0)
	s_setprio 1
	s_waitcnt lgkmcnt(0)
	v_mfma_f32_16x16x32_bf16 v[62:65], v[140:143], v[168:171], v[62:65]
	v_mfma_f32_16x16x32_bf16 v[58:61], v[158:161], v[168:171], v[58:61]
	v_mfma_f32_16x16x32_bf16 v[50:53], v[140:143], v[176:179], v[50:53]
	v_mfma_f32_16x16x32_bf16 v[42:45], v[158:161], v[176:179], v[42:45]
	v_mfma_f32_16x16x32_bf16 v[34:37], v[140:143], v[184:187], v[34:37]
	v_mfma_f32_16x16x32_bf16 v[26:29], v[158:161], v[184:187], v[26:29]
	v_mfma_f32_16x16x32_bf16 v[18:21], v[140:143], v[192:195], v[18:21]
	v_mfma_f32_16x16x32_bf16 v[10:13], v[158:161], v[192:195], v[10:13]
	v_mfma_f32_16x16x32_bf16 v[62:65], v[154:157], v[172:175], v[62:65]
	v_mfma_f32_16x16x32_bf16 v[58:61], v[164:167], v[172:175], v[58:61]
	v_mfma_f32_16x16x32_bf16 v[50:53], v[154:157], v[180:183], v[50:53]
	v_mfma_f32_16x16x32_bf16 v[42:45], v[164:167], v[180:183], v[42:45]
	v_mfma_f32_16x16x32_bf16 v[34:37], v[154:157], v[188:191], v[34:37]
	v_mfma_f32_16x16x32_bf16 v[26:29], v[164:167], v[188:191], v[26:29]
	v_mfma_f32_16x16x32_bf16 v[18:21], v[154:157], v[198:201], v[18:21]
	v_mfma_f32_16x16x32_bf16 v[10:13], v[164:167], v[198:201], v[10:13]
	s_setprio 0
	s_barrier
; #define PG8_STAGE(bufoff, gbase, voff) do { _Pragma("unroll") for (int _i = 0; _i < 2; ++_i) \
;         __builtin_amdgcn_global_load_lds((const unsigned*)((const char*)(gbase) + (voff)[_i]), (LAS unsigned*)(lds + (bufoff) + ldsw + _i * 8192), 16, 0, 0); } while (0)
; #define PG8_LDA(dst, b, h) do { _Pragma("unroll") for (int m = 0; m < 4; ++m) _Pragma("unroll") for (int k = 0; k < 2; ++k) dst[m][k] = *(const LAS bf16x8*)(lds + PG8_SA(b, h) + aoff + m * 2048 + k * 1024); } while (0)
; #define PG8_LDB(dst, b, h) do { _Pragma("unroll") for (int n = 0; n < 2; ++n) _Pragma("unroll") for (int k = 0; k < 2; ++k) dst[n][k] = *(const LAS bf16x8*)(lds + PG8_SB(b, h) + boff + n * 2048 + k * 1024); } while (0)
; #define PG8_MMA(ai, bj, At, Bt) do { __builtin_amdgcn_s_setprio(1); _Pragma("unroll") for (int m = 0; m < 4; ++m) _Pragma("unroll") for (int n = 0; n < 2; ++n) _Pragma("unroll") for (int k = 0; k < 2; ++k) \
;         acc[ai][bj][m][n] = __builtin_amdgcn_mfma_f32_16x16x32_bf16(Bt[n][k], At[m][k], acc[ai][bj][m][n], 0, 0, 0); __builtin_amdgcn_s_setprio(0); } while (0)
; #define PG8_WAIT_V(n) asm volatile("s_waitcnt vmcnt(" #n ")" ::: "memory")
; #define PG8_WAIT_L(n) asm volatile("s_waitcnt lgkmcnt(" #n ")" ::: "memory")
; #define PG8_BAR __builtin_amdgcn_s_barrier()
; #define PG8_SCHED __builtin_amdgcn_sched_barrier(0)
; template <class Epi, class Sched>
; DI void gemm_phase(LAS unsigned char* lds, const Gemm g, const Sched& S, const Epi& E) {
;     ...
;             PG8_STAGE(PG8_SB(0, 1), b2 + hstep, voffB);
;             PG8_WAIT_V(6); PG8_BAR; PG8_MMA(1, 1, At, B1); PG8_BAR;
;             PG8_LDB(B0, 1, 0); PG8_SCHED; PG8_LDA(At, 1, 0); PG8_STAGE(PG8_SA(0, 1), a2 + hstep, voffA);
;             PG8_WAIT_L(8); PG8_BAR; PG8_WAIT_L(0); PG8_MMA(0, 0, At, B0); PG8_BAR; PG8_SCHED;
;             PG8_LDB(B1, 1, 1); PG8_STAGE(PG8_SB(1, 0), b3, voffB);
;             PG8_BAR; PG8_WAIT_L(0); PG8_MMA(0, 1, At, B1); PG8_BAR;
;             PG8_LDA(At, 1, 1); PG8_STAGE(PG8_SA(1, 0), a3, voffA);
;             PG8_BAR; PG8_WAIT_L(0); PG8_MMA(1, 0, At, B0); PG8_BAR; PG8_SCHED;
	s_add_u32 s72, s24, 0x40000
	s_addc_u32 s73, s25, 0
	s_add_i32 s67, s35, s12
	v_lshl_add_u64 v[140:141], s[72:73], 0, v[132:133]
	s_mov_b32 m0, s67
	s_nop 0
	global_load_lds_dwordx4 v[140:141], off
	v_lshl_add_u64 v[140:141], s[72:73], 0, v[130:131]
	s_add_i32 m0, s67, 0x2000
	s_nop 0
	global_load_lds_dwordx4 v[140:141], off
	s_waitcnt vmcnt(6)
	s_barrier
	s_setprio 1
	v_mfma_f32_16x16x32_bf16 v[54:57], v[202:205], v[168:171], v[54:57]
	v_mfma_f32_16x16x32_bf16 v[46:49], v[210:213], v[168:171], v[46:49]
	v_mfma_f32_16x16x32_bf16 v[38:41], v[202:205], v[176:179], v[38:41]
	v_mfma_f32_16x16x32_bf16 v[30:33], v[210:213], v[176:179], v[30:33]
	v_mfma_f32_16x16x32_bf16 v[22:25], v[202:205], v[184:187], v[22:25]
	v_mfma_f32_16x16x32_bf16 v[14:17], v[210:213], v[184:187], v[14:17]
	v_mfma_f32_16x16x32_bf16 v[6:9], v[202:205], v[192:195], v[6:9]
	v_mfma_f32_16x16x32_bf16 v[2:5], v[210:213], v[192:195], v[2:5]
	v_mfma_f32_16x16x32_bf16 v[54:57], v[206:209], v[172:175], v[54:57]
	v_mfma_f32_16x16x32_bf16 v[46:49], v[214:217], v[172:175], v[46:49]
	v_mfma_f32_16x16x32_bf16 v[38:41], v[206:209], v[180:183], v[38:41]
	v_mfma_f32_16x16x32_bf16 v[30:33], v[214:217], v[180:183], v[30:33]
	v_mfma_f32_16x16x32_bf16 v[22:25], v[206:209], v[188:191], v[22:25]
	v_mfma_f32_16x16x32_bf16 v[14:17], v[214:217], v[188:191], v[14:17]
	v_mfma_f32_16x16x32_bf16 v[6:9], v[206:209], v[198:201], v[6:9]
	v_mfma_f32_16x16x32_bf16 v[2:5], v[214:217], v[198:201], v[2:5]
	s_setprio 0
	s_add_i32 s67, 0, 0x18000
	v_add_u32_e32 v134, s67, v145
	s_barrier
	ds_read_b128 v[140:143], v134
	ds_read_b128 v[154:157], v134 offset:1024
	ds_read_b128 v[158:161], v134 offset:2048
	ds_read_b128 v[164:167], v134 offset:3072
	s_add_u32 s26, s26, 0x40000
	s_addc_u32 s27, s27, 0
	s_mov_b32 m0, s29
	v_lshl_add_u64 v[202:203], s[26:27], 0, v[132:133]
	ds_read_b128 v[168:171], v148 offset:32768
	ds_read_b128 v[172:175], v148 offset:33792
	ds_read_b128 v[176:179], v148 offset:34816
	ds_read_b128 v[180:183], v148 offset:35840
	ds_read_b128 v[184:187], v148 offset:36864
	ds_read_b128 v[188:191], v148 offset:37888
	ds_read_b128 v[192:195], v148 offset:38912
	ds_read_b128 v[198:201], v148 offset:39936
	global_load_lds_dwordx4 v[202:203], off
	v_lshl_add_u64 v[202:203], s[26:27], 0, v[130:131]
	s_mov_b32 m0, s30
	s_nop 0
	global_load_lds_dwordx4 v[202:203], off
	s_waitcnt lgkmcnt(8)
	s_barrier
	s_waitcnt lgkmcnt(0)
	s_setprio 1
	s_waitcnt lgkmcnt(0)
	v_mfma_f32_16x16x32_bf16 v[126:129], v[140:143], v[168:171], v[126:129]
	v_mfma_f32_16x16x32_bf16 v[122:125], v[158:161], v[168:171], v[122:125]
	v_mfma_f32_16x16x32_bf16 v[114:117], v[140:143], v[176:179], v[114:117]
	v_mfma_f32_16x16x32_bf16 v[106:109], v[158:161], v[176:179], v[106:109]
	v_mfma_f32_16x16x32_bf16 v[98:101], v[140:143], v[184:187], v[98:101]
	v_mfma_f32_16x16x32_bf16 v[90:93], v[158:161], v[184:187], v[90:93]
	v_mfma_f32_16x16x32_bf16 v[82:85], v[140:143], v[192:195], v[82:85]
	v_mfma_f32_16x16x32_bf16 v[74:77], v[158:161], v[192:195], v[74:77]
	v_mfma_f32_16x16x32_bf16 v[126:129], v[154:157], v[172:175], v[126:129]
	v_mfma_f32_16x16x32_bf16 v[122:125], v[164:167], v[172:175], v[122:125]
	v_mfma_f32_16x16x32_bf16 v[114:117], v[154:157], v[180:183], v[114:117]
	v_mfma_f32_16x16x32_bf16 v[106:109], v[164:167], v[180:183], v[106:109]
	v_mfma_f32_16x16x32_bf16 v[98:101], v[154:157], v[188:191], v[98:101]
	v_mfma_f32_16x16x32_bf16 v[90:93], v[164:167], v[188:191], v[90:93]
	v_mfma_f32_16x16x32_bf16 v[82:85], v[154:157], v[198:201], v[82:85]
	v_mfma_f32_16x16x32_bf16 v[74:77], v[164:167], v[198:201], v[74:77]
	s_setprio 0
	s_barrier
	s_add_i32 s26, 0, 0x1c000
	s_add_i32 s27, s67, s12
	v_add_u32_e32 v134, s26, v145
	v_lshl_add_u64 v[150:151], v[150:151], 0, s[10:11]
	s_mov_b32 m0, s27
	ds_read_b128 v[202:205], v134
	ds_read_b128 v[206:209], v134 offset:1024
	ds_read_b128 v[210:213], v134 offset:2048
	ds_read_b128 v[214:217], v134 offset:3072
	global_load_lds_dwordx4 v[150:151], off
	v_lshl_add_u64 v[150:151], v[218:219], 0, s[10:11]
	s_add_i32 m0, s27, 0x2000
	s_nop 0
	global_load_lds_dwordx4 v[150:151], off
	s_barrier
	s_waitcnt lgkmcnt(0)
	s_setprio 1
	s_waitcnt lgkmcnt(0)
	v_mfma_f32_16x16x32_bf16 v[118:121], v[202:205], v[168:171], v[118:121]
	v_mfma_f32_16x16x32_bf16 v[110:113], v[210:213], v[168:171], v[110:113]
	v_mfma_f32_16x16x32_bf16 v[102:105], v[202:205], v[176:179], v[102:105]
	v_mfma_f32_16x16x32_bf16 v[94:97], v[210:213], v[176:179], v[94:97]
	v_mfma_f32_16x16x32_bf16 v[86:89], v[202:205], v[184:187], v[86:89]
	v_mfma_f32_16x16x32_bf16 v[78:81], v[210:213], v[184:187], v[78:81]
	v_mfma_f32_16x16x32_bf16 v[70:73], v[202:205], v[192:195], v[70:73]
	v_mfma_f32_16x16x32_bf16 v[66:69], v[210:213], v[192:195], v[66:69]
	v_mfma_f32_16x16x32_bf16 v[118:121], v[206:209], v[172:175], v[118:121]
	v_mfma_f32_16x16x32_bf16 v[110:113], v[214:217], v[172:175], v[110:113]
	v_mfma_f32_16x16x32_bf16 v[102:105], v[206:209], v[180:183], v[102:105]
	v_mfma_f32_16x16x32_bf16 v[94:97], v[214:217], v[180:183], v[94:97]
	v_mfma_f32_16x16x32_bf16 v[86:89], v[206:209], v[188:191], v[86:89]
	v_mfma_f32_16x16x32_bf16 v[78:81], v[214:217], v[188:191], v[78:81]
	v_mfma_f32_16x16x32_bf16 v[70:73], v[206:209], v[198:201], v[70:73]
	v_mfma_f32_16x16x32_bf16 v[66:69], v[214:217], v[198:201], v[66:69]
	s_setprio 0
	s_mov_b32 m0, s33
	v_lshl_add_u64 v[150:151], v[220:221], 0, s[10:11]
	s_barrier
	ds_read_b128 v[168:171], v148 offset:49152
	ds_read_b128 v[172:175], v148 offset:50176
	ds_read_b128 v[176:179], v148 offset:51200
	ds_read_b128 v[180:183], v148 offset:52224
	ds_read_b128 v[184:187], v148 offset:53248
	ds_read_b128 v[188:191], v148 offset:54272
	ds_read_b128 v[192:195], v148 offset:55296
	ds_read_b128 v[198:201], v148 offset:56320
	global_load_lds_dwordx4 v[150:151], off
	v_lshl_add_u64 v[150:151], v[222:223], 0, s[10:11]
	s_mov_b32 m0, s34
	s_nop 0
	global_load_lds_dwordx4 v[150:151], off
	s_barrier
; DI unsigned pk_bf16(float a, float b) { f32x2 v = {a, b}; bf2_t r = __builtin_convertvector(v, bf2_t); return __builtin_bit_cast(unsigned, r); }
; DI float bflo(unsigned u) { return __uint_as_float(u << 16); }
; DI float bfhi(unsigned u) { return __uint_as_float(u & 0xffff0000u); }
; #define PG8_STAGE(bufoff, gbase, voff) do { _Pragma("unroll") for (int _i = 0; _i < 2; ++_i) \
;         __builtin_amdgcn_global_load_lds((const unsigned*)((const char*)(gbase) + (voff)[_i]), (LAS unsigned*)(lds + (bufoff) + ldsw + _i * 8192), 16, 0, 0); } while (0)
; #define PG8_MMA(ai, bj, At, Bt) do { __builtin_amdgcn_s_setprio(1); _Pragma("unroll") for (int m = 0; m < 4; ++m) _Pragma("unroll") for (int n = 0; n < 2; ++n) _Pragma("unroll") for (int k = 0; k < 2; ++k) \
;         acc[ai][bj][m][n] = __builtin_amdgcn_mfma_f32_16x16x32_bf16(Bt[n][k], At[m][k], acc[ai][bj][m][n], 0, 0, 0); __builtin_amdgcn_s_setprio(0); } while (0)
; #define PG8_WAIT_V(n) asm volatile("s_waitcnt vmcnt(" #n ")" ::: "memory")
; #define PG8_WAIT_L(n) asm volatile("s_waitcnt lgkmcnt(" #n ")" ::: "memory")
;     DI void operator()(const f32x4 (&acc)[2][2][4][2], const Unit& u, int wr, int wc, int fr, int fq) const {
;         const int row0 = u.pm * BM + wr * 64 + fr, col0 = u.pn * BM + wc * 32 + 4 * fq;
; #pragma unroll
;         for (int ai = 0; ai < 2; ++ai)
; #pragma unroll
;             for (int m = 0; m < 4; ++m) { const size_t o = (size_t)(row0 + ai * HALF + m * 16) * 1024 + col0;
; #pragma unroll
;                 for (int bj = 0; bj < 2; ++bj)
; #pragma unroll
;                     for (int n = 0; n < 2; ++n) { const size_t oo = o + bj * HALF + n * 16; f32x4 rv;
;                         if (RES_BF16) { const u32x2 t = *(const u32x2*)((const bf16_t*)res + oo); rv = (f32x4){bflo(t.x), bfhi(t.x), bflo(t.y), bfhi(t.y)}; }
;                         else rv = *(const f32x4*)((const float*)res + oo);
;                         const f32x4 v = acc[ai][bj][m][n] + rv; u32x2 w; w.x = pk_bf16(v.x, v.y); w.y = pk_bf16(v.z, v.w);
; template <class Epi, class Sched>
; DI void gemm_phase(LAS unsigned char* lds, const Gemm g, const Sched& S, const Epi& E) {
;     ...
;             PG8_BAR; PG8_WAIT_L(0); PG8_MMA(1, 0, At, B0); PG8_BAR; PG8_SCHED;
;             PG8_STAGE(PG8_SB(1, 1), b3 + hstep, voffB);
;             PG8_WAIT_V(6); PG8_BAR; PG8_MMA(1, 1, At, B1); PG8_BAR;
	s_waitcnt lgkmcnt(0)
	s_setprio 1
	s_waitcnt lgkmcnt(0)
	v_mfma_f32_16x16x32_bf16 v[62:65], v[140:143], v[168:171], v[62:65]
	v_mfma_f32_16x16x32_bf16 v[58:61], v[158:161], v[168:171], v[58:61]
	v_mfma_f32_16x16x32_bf16 v[50:53], v[140:143], v[176:179], v[50:53]
	v_mfma_f32_16x16x32_bf16 v[42:45], v[158:161], v[176:179], v[42:45]
	v_mfma_f32_16x16x32_bf16 v[34:37], v[140:143], v[184:187], v[34:37]
	v_mfma_f32_16x16x32_bf16 v[26:29], v[158:161], v[184:187], v[26:29]
	v_mfma_f32_16x16x32_bf16 v[18:21], v[140:143], v[192:195], v[18:21]
	v_mfma_f32_16x16x32_bf16 v[10:13], v[158:161], v[192:195], v[10:13]
	v_mfma_f32_16x16x32_bf16 v[62:65], v[154:157], v[172:175], v[62:65]
	v_mfma_f32_16x16x32_bf16 v[58:61], v[164:167], v[172:175], v[58:61]
	v_mfma_f32_16x16x32_bf16 v[50:53], v[154:157], v[180:183], v[50:53]
	v_mfma_f32_16x16x32_bf16 v[42:45], v[164:167], v[180:183], v[42:45]
	v_mfma_f32_16x16x32_bf16 v[34:37], v[154:157], v[188:191], v[34:37]
	v_mfma_f32_16x16x32_bf16 v[26:29], v[164:167], v[188:191], v[26:29]
	v_mfma_f32_16x16x32_bf16 v[18:21], v[154:157], v[198:201], v[18:21]
	v_mfma_f32_16x16x32_bf16 v[10:13], v[164:167], v[198:201], v[10:13]
	s_setprio 0
	s_barrier
	s_add_u32 s24, s24, 0x40080
	s_addc_u32 s25, s25, 0
	s_add_i32 s26, s26, s12
	v_lshl_add_u64 v[140:141], s[24:25], 0, v[132:133]
	s_mov_b32 m0, s26
	s_nop 0
	global_load_lds_dwordx4 v[140:141], off
	v_lshl_add_u64 v[140:141], s[24:25], 0, v[130:131]
	s_add_i32 m0, s26, 0x2000
	s_nop 0
	global_load_lds_dwordx4 v[140:141], off
	s_waitcnt vmcnt(6)
	s_barrier
	s_setprio 1
	v_mfma_f32_16x16x32_bf16 v[54:57], v[202:205], v[168:171], v[54:57]
	v_mfma_f32_16x16x32_bf16 v[46:49], v[210:213], v[168:171], v[46:49]
	v_mfma_f32_16x16x32_bf16 v[38:41], v[202:205], v[176:179], v[38:41]
	v_mfma_f32_16x16x32_bf16 v[30:33], v[210:213], v[176:179], v[30:33]
	v_mfma_f32_16x16x32_bf16 v[22:25], v[202:205], v[184:187], v[22:25]
	v_mfma_f32_16x16x32_bf16 v[14:17], v[210:213], v[184:187], v[14:17]
	v_mfma_f32_16x16x32_bf16 v[6:9], v[202:205], v[192:195], v[6:9]
	v_mfma_f32_16x16x32_bf16 v[2:5], v[210:213], v[192:195], v[2:5]
	v_mfma_f32_16x16x32_bf16 v[54:57], v[206:209], v[172:175], v[54:57]
	v_mfma_f32_16x16x32_bf16 v[46:49], v[214:217], v[172:175], v[46:49]
	v_mfma_f32_16x16x32_bf16 v[38:41], v[206:209], v[180:183], v[38:41]
	v_mfma_f32_16x16x32_bf16 v[30:33], v[214:217], v[180:183], v[30:33]
	v_mfma_f32_16x16x32_bf16 v[22:25], v[206:209], v[188:191], v[22:25]
	v_mfma_f32_16x16x32_bf16 v[14:17], v[214:217], v[188:191], v[14:17]
	v_mfma_f32_16x16x32_bf16 v[6:9], v[206:209], v[198:201], v[6:9]
	v_mfma_f32_16x16x32_bf16 v[2:5], v[214:217], v[198:201], v[2:5]
	s_setprio 0
	s_add_i32 s66, s66, 2
	s_add_u32 s22, s22, 0x100
	s_addc_u32 s23, s23, 0
	s_add_u32 s58, s58, 0x100
	s_addc_u32 s59, s59, 0
	s_cmp_gt_u32 s66, 13
	s_barrier
	s_cbranch_scc0 .LBB0_1007
	v_lshl_add_u32 v224, s43, 8, v144
	v_lshl_or_b32 v243, s42, 8, v146
	v_lshl_or_b32 v224, v224, 10, v243
	s_and_b64 vcc, exec, s[20:21]
	s_mov_b32 s42, s40
	s_mov_b32 s43, s41
	s_mov_b64 s[22:23], 0x2c000
	v_lshlrev_b32_e32 v225, 2, v224
	v_lshlrev_b32_e32 v233, 1, v224
	v_add_u32_e32 v234, 0x4000, v224
	v_lshlrev_b32_e32 v226, 2, v234
	v_lshlrev_b32_e32 v234, 1, v234
	v_add_u32_e32 v235, 0x8000, v224
	v_lshlrev_b32_e32 v227, 2, v235
	v_lshlrev_b32_e32 v235, 1, v235
	v_add_u32_e32 v236, 0xc000, v224
	v_lshlrev_b32_e32 v228, 2, v236
	v_lshlrev_b32_e32 v236, 1, v236
	v_add_u32_e32 v237, 0x20000, v224
	v_lshlrev_b32_e32 v229, 2, v237
	v_lshlrev_b32_e32 v237, 1, v237
	v_add_u32_e32 v240, 0x24000, v224
	v_lshlrev_b32_e32 v230, 2, v240
	v_lshlrev_b32_e32 v240, 1, v240
	v_add_u32_e32 v241, 0x28000, v224
	v_lshlrev_b32_e32 v231, 2, v241
	v_lshlrev_b32_e32 v241, 1, v241
	v_add_u32_e32 v242, 0x2c000, v224
	v_lshlrev_b32_e32 v232, 2, v242
	v_lshlrev_b32_e32 v242, 1, v242
	global_load_dwordx4 v[140:143], v225, s[60:61]
	global_load_dwordx4 v[154:157], v225, s[60:61] offset:64
	global_load_dwordx4 v[158:161], v225, s[60:61] offset:512
	global_load_dwordx4 v[164:167], v225, s[60:61] offset:576
	global_load_dwordx4 v[168:171], v226, s[60:61]
	global_load_dwordx4 v[172:175], v226, s[60:61] offset:64
	global_load_dwordx4 v[176:179], v226, s[60:61] offset:512
	global_load_dwordx4 v[180:183], v226, s[60:61] offset:576
	global_load_dwordx4 v[184:187], v227, s[60:61]
	global_load_dwordx4 v[188:191], v227, s[60:61] offset:64
	global_load_dwordx4 v[192:195], v227, s[60:61] offset:512
	global_load_dwordx4 v[198:201], v227, s[60:61] offset:576
	global_load_dwordx4 v[202:205], v228, s[60:61]
	global_load_dwordx4 v[206:209], v228, s[60:61] offset:64
	global_load_dwordx4 v[210:213], v228, s[60:61] offset:512
	global_load_dwordx4 v[214:217], v228, s[60:61] offset:576
	s_waitcnt vmcnt(12)
	v_pk_add_f32 v[128:129], v[128:129], v[142:143]
	v_pk_add_f32 v[126:127], v[126:127], v[140:141]
	v_pk_add_f32 v[124:125], v[124:125], v[156:157]
	v_pk_add_f32 v[122:123], v[122:123], v[154:155]
	v_pk_add_f32 v[120:121], v[120:121], v[160:161]
	v_pk_add_f32 v[118:119], v[118:119], v[158:159]
	v_pk_add_f32 v[112:113], v[112:113], v[166:167]
	v_pk_add_f32 v[110:111], v[110:111], v[164:165]
	v_cvt_pk_bf16_f32 v126, v126, v127
	v_cvt_pk_bf16_f32 v127, v128, v129
	v_cvt_pk_bf16_f32 v122, v122, v123
	v_cvt_pk_bf16_f32 v123, v124, v125
	v_cvt_pk_bf16_f32 v118, v118, v119
	v_cvt_pk_bf16_f32 v119, v120, v121
	v_cvt_pk_bf16_f32 v110, v110, v111
	v_cvt_pk_bf16_f32 v111, v112, v113
	global_store_dwordx2 v233, v[126:127], s[48:49]
	global_store_dwordx2 v233, v[122:123], s[48:49] offset:32
	global_store_dwordx2 v233, v[118:119], s[48:49] offset:256
	global_store_dwordx2 v233, v[110:111], s[48:49] offset:288
	global_load_dwordx4 v[140:143], v229, s[60:61]
	global_load_dwordx4 v[154:157], v229, s[60:61] offset:64
	global_load_dwordx4 v[158:161], v229, s[60:61] offset:512
	global_load_dwordx4 v[164:167], v229, s[60:61] offset:576
	s_waitcnt vmcnt(16)
; DI unsigned pk_bf16(float a, float b) { f32x2 v = {a, b}; bf2_t r = __builtin_convertvector(v, bf2_t); return __builtin_bit_cast(unsigned, r); }
; DI float bflo(unsigned u) { return __uint_as_float(u << 16); }
; DI float bfhi(unsigned u) { return __uint_as_float(u & 0xffff0000u); }
;     DI void operator()(const f32x4 (&acc)[2][2][4][2], const Unit& u, int wr, int wc, int fr, int fq) const {
;     ...
;             for (int m = 0; m < 4; ++m) { const size_t o = (size_t)(row0 + ai * HALF + m * 16) * 1024 + col0;
; #pragma unroll
;                 for (int bj = 0; bj < 2; ++bj)
; #pragma unroll
;                     for (int n = 0; n < 2; ++n) { const size_t oo = o + bj * HALF + n * 16; f32x4 rv;
;                         if (RES_BF16) { const u32x2 t = *(const u32x2*)((const bf16_t*)res + oo); rv = (f32x4){bflo(t.x), bfhi(t.x), bflo(t.y), bfhi(t.y)}; }
;                         else rv = *(const f32x4*)((const float*)res + oo);
;                         const f32x4 v = acc[ai][bj][m][n] + rv; u32x2 w; w.x = pk_bf16(v.x, v.y); w.y = pk_bf16(v.z, v.w);
;                         *(u32x2*)(O + oo) = w; } }
	v_pk_add_f32 v[116:117], v[116:117], v[170:171]
	v_pk_add_f32 v[114:115], v[114:115], v[168:169]
	v_pk_add_f32 v[108:109], v[108:109], v[174:175]
	v_pk_add_f32 v[106:107], v[106:107], v[172:173]
	v_pk_add_f32 v[104:105], v[104:105], v[178:179]
	v_pk_add_f32 v[102:103], v[102:103], v[176:177]
	v_pk_add_f32 v[96:97], v[96:97], v[182:183]
	v_pk_add_f32 v[94:95], v[94:95], v[180:181]
	v_cvt_pk_bf16_f32 v114, v114, v115
	v_cvt_pk_bf16_f32 v115, v116, v117
	v_cvt_pk_bf16_f32 v106, v106, v107
	v_cvt_pk_bf16_f32 v107, v108, v109
	v_cvt_pk_bf16_f32 v102, v102, v103
	v_cvt_pk_bf16_f32 v103, v104, v105
	v_cvt_pk_bf16_f32 v94, v94, v95
	v_cvt_pk_bf16_f32 v95, v96, v97
	global_store_dwordx2 v234, v[114:115], s[48:49]
	global_store_dwordx2 v234, v[106:107], s[48:49] offset:32
	global_store_dwordx2 v234, v[102:103], s[48:49] offset:256
	global_store_dwordx2 v234, v[94:95], s[48:49] offset:288
	global_load_dwordx4 v[168:171], v230, s[60:61]
	global_load_dwordx4 v[172:175], v230, s[60:61] offset:64
	global_load_dwordx4 v[176:179], v230, s[60:61] offset:512
	global_load_dwordx4 v[180:183], v230, s[60:61] offset:576
	s_waitcnt vmcnt(20)
	v_pk_add_f32 v[100:101], v[100:101], v[186:187]
	v_pk_add_f32 v[98:99], v[98:99], v[184:185]
	v_pk_add_f32 v[92:93], v[92:93], v[190:191]
	v_pk_add_f32 v[90:91], v[90:91], v[188:189]
	v_pk_add_f32 v[88:89], v[88:89], v[194:195]
	v_pk_add_f32 v[86:87], v[86:87], v[192:193]
	v_pk_add_f32 v[80:81], v[80:81], v[200:201]
	v_pk_add_f32 v[78:79], v[78:79], v[198:199]
	v_cvt_pk_bf16_f32 v98, v98, v99
	v_cvt_pk_bf16_f32 v99, v100, v101
	v_cvt_pk_bf16_f32 v90, v90, v91
	v_cvt_pk_bf16_f32 v91, v92, v93
	v_cvt_pk_bf16_f32 v86, v86, v87
	v_cvt_pk_bf16_f32 v87, v88, v89
	v_cvt_pk_bf16_f32 v78, v78, v79
	v_cvt_pk_bf16_f32 v79, v80, v81
	global_store_dwordx2 v235, v[98:99], s[48:49]
	global_store_dwordx2 v235, v[90:91], s[48:49] offset:32
	global_store_dwordx2 v235, v[86:87], s[48:49] offset:256
	global_store_dwordx2 v235, v[78:79], s[48:49] offset:288
	global_load_dwordx4 v[184:187], v231, s[60:61]
	global_load_dwordx4 v[188:191], v231, s[60:61] offset:64
	global_load_dwordx4 v[192:195], v231, s[60:61] offset:512
	global_load_dwordx4 v[198:201], v231, s[60:61] offset:576
	s_waitcnt vmcnt(24)
	v_pk_add_f32 v[84:85], v[84:85], v[204:205]
	v_pk_add_f32 v[82:83], v[82:83], v[202:203]
	v_pk_add_f32 v[76:77], v[76:77], v[208:209]
	v_pk_add_f32 v[74:75], v[74:75], v[206:207]
	v_pk_add_f32 v[72:73], v[72:73], v[212:213]
	v_pk_add_f32 v[70:71], v[70:71], v[210:211]
	v_pk_add_f32 v[68:69], v[68:69], v[216:217]
	v_pk_add_f32 v[66:67], v[66:67], v[214:215]
	v_cvt_pk_bf16_f32 v82, v82, v83
	v_cvt_pk_bf16_f32 v83, v84, v85
	v_cvt_pk_bf16_f32 v74, v74, v75
	v_cvt_pk_bf16_f32 v75, v76, v77
	v_cvt_pk_bf16_f32 v70, v70, v71
	v_cvt_pk_bf16_f32 v71, v72, v73
	v_cvt_pk_bf16_f32 v66, v66, v67
	v_cvt_pk_bf16_f32 v67, v68, v69
	global_store_dwordx2 v236, v[82:83], s[48:49]
	global_store_dwordx2 v236, v[74:75], s[48:49] offset:32
	global_store_dwordx2 v236, v[70:71], s[48:49] offset:256
	global_store_dwordx2 v236, v[66:67], s[48:49] offset:288
	global_load_dwordx4 v[202:205], v232, s[60:61]
	global_load_dwordx4 v[206:209], v232, s[60:61] offset:64
	global_load_dwordx4 v[210:213], v232, s[60:61] offset:512
	global_load_dwordx4 v[214:217], v232, s[60:61] offset:576
	s_waitcnt vmcnt(24)
	v_pk_add_f32 v[64:65], v[64:65], v[142:143]
	v_pk_add_f32 v[62:63], v[62:63], v[140:141]
	v_pk_add_f32 v[60:61], v[60:61], v[156:157]
	v_pk_add_f32 v[58:59], v[58:59], v[154:155]
	v_pk_add_f32 v[56:57], v[56:57], v[160:161]
	v_pk_add_f32 v[54:55], v[54:55], v[158:159]
	v_pk_add_f32 v[48:49], v[48:49], v[166:167]
	v_pk_add_f32 v[46:47], v[46:47], v[164:165]
	v_cvt_pk_bf16_f32 v62, v62, v63
	v_cvt_pk_bf16_f32 v63, v64, v65
	v_cvt_pk_bf16_f32 v58, v58, v59
	v_cvt_pk_bf16_f32 v59, v60, v61
	v_cvt_pk_bf16_f32 v54, v54, v55
	v_cvt_pk_bf16_f32 v55, v56, v57
	v_cvt_pk_bf16_f32 v46, v46, v47
	v_cvt_pk_bf16_f32 v47, v48, v49
	global_store_dwordx2 v237, v[62:63], s[48:49]
	global_store_dwordx2 v237, v[58:59], s[48:49] offset:32
	global_store_dwordx2 v237, v[54:55], s[48:49] offset:256
	global_store_dwordx2 v237, v[46:47], s[48:49] offset:288
	s_waitcnt vmcnt(20)
	v_pk_add_f32 v[52:53], v[52:53], v[170:171]
	v_pk_add_f32 v[50:51], v[50:51], v[168:169]
	v_pk_add_f32 v[44:45], v[44:45], v[174:175]
	v_pk_add_f32 v[42:43], v[42:43], v[172:173]
	v_pk_add_f32 v[40:41], v[40:41], v[178:179]
	v_pk_add_f32 v[38:39], v[38:39], v[176:177]
	v_pk_add_f32 v[32:33], v[32:33], v[182:183]
	v_pk_add_f32 v[30:31], v[30:31], v[180:181]
	v_cvt_pk_bf16_f32 v50, v50, v51
	v_cvt_pk_bf16_f32 v51, v52, v53
	v_cvt_pk_bf16_f32 v42, v42, v43
	v_cvt_pk_bf16_f32 v43, v44, v45
	v_cvt_pk_bf16_f32 v38, v38, v39
	v_cvt_pk_bf16_f32 v39, v40, v41
	v_cvt_pk_bf16_f32 v30, v30, v31
	v_cvt_pk_bf16_f32 v31, v32, v33
	global_store_dwordx2 v240, v[50:51], s[48:49]
	global_store_dwordx2 v240, v[42:43], s[48:49] offset:32
	global_store_dwordx2 v240, v[38:39], s[48:49] offset:256
	global_store_dwordx2 v240, v[30:31], s[48:49] offset:288
	s_waitcnt vmcnt(16)
	v_pk_add_f32 v[36:37], v[36:37], v[186:187]
	v_pk_add_f32 v[34:35], v[34:35], v[184:185]
	v_pk_add_f32 v[28:29], v[28:29], v[190:191]
	v_pk_add_f32 v[26:27], v[26:27], v[188:189]
	v_pk_add_f32 v[24:25], v[24:25], v[194:195]
	v_pk_add_f32 v[22:23], v[22:23], v[192:193]
	v_pk_add_f32 v[16:17], v[16:17], v[200:201]
	v_pk_add_f32 v[14:15], v[14:15], v[198:199]
	v_cvt_pk_bf16_f32 v34, v34, v35
	v_cvt_pk_bf16_f32 v35, v36, v37
	v_cvt_pk_bf16_f32 v26, v26, v27
	v_cvt_pk_bf16_f32 v27, v28, v29
	v_cvt_pk_bf16_f32 v22, v22, v23
	v_cvt_pk_bf16_f32 v23, v24, v25
	v_cvt_pk_bf16_f32 v14, v14, v15
	v_cvt_pk_bf16_f32 v15, v16, v17
	global_store_dwordx2 v241, v[34:35], s[48:49]
	global_store_dwordx2 v241, v[26:27], s[48:49] offset:32
	global_store_dwordx2 v241, v[22:23], s[48:49] offset:256
	global_store_dwordx2 v241, v[14:15], s[48:49] offset:288
	s_waitcnt vmcnt(12)
	v_pk_add_f32 v[20:21], v[20:21], v[204:205]
	v_pk_add_f32 v[18:19], v[18:19], v[202:203]
	v_pk_add_f32 v[12:13], v[12:13], v[208:209]
	v_pk_add_f32 v[10:11], v[10:11], v[206:207]
	v_pk_add_f32 v[8:9], v[8:9], v[212:213]
	v_pk_add_f32 v[6:7], v[6:7], v[210:211]
	v_pk_add_f32 v[4:5], v[4:5], v[216:217]
	v_pk_add_f32 v[2:3], v[2:3], v[214:215]
	v_cvt_pk_bf16_f32 v18, v18, v19
	v_cvt_pk_bf16_f32 v19, v20, v21
	v_cvt_pk_bf16_f32 v10, v10, v11
	v_cvt_pk_bf16_f32 v11, v12, v13
	v_cvt_pk_bf16_f32 v6, v6, v7
	v_cvt_pk_bf16_f32 v7, v8, v9
	v_cvt_pk_bf16_f32 v2, v2, v3
	v_cvt_pk_bf16_f32 v3, v4, v5
	global_store_dwordx2 v242, v[18:19], s[48:49]
	global_store_dwordx2 v242, v[10:11], s[48:49] offset:32
	global_store_dwordx2 v242, v[6:7], s[48:49] offset:256
	global_store_dwordx2 v242, v[2:3], s[48:49] offset:288
	s_cbranch_vccz .LBB0_1006
	s_waitcnt vmcnt(0)
	s_cmpk_gt_u32 s3, 0xff
	s_cbranch_scc1 .LBB0_1011
	s_barrier

; #define LAS __attribute__((address_space(3)))
; #define MFMA32(a, b, c) __builtin_amdgcn_mfma_f32_32x32x16_bf16((a), (b), (c), 0, 0, 0)
; #define RET_DMA_B(n) do { const unsigned char* g_ = gblk + (size_t)(n) * ROP_STRIDE; RET_CP(32768, 40960, 4); } while (0)
; DI void ret_scan_prompt(const Params& p, int item, unsigned char* smem) {
;     ...
;         RET_DMA_B(n);
;         f32x16 O[2];
; #pragma unroll
;         for (int rt = 0; rt < 2; ++rt)
; #pragma unroll
;             for (int i = 0; i < 16; ++i) O[rt][i] = 0.f;
;         const LAS unsigned short* vcol = (const LAS unsigned short*)(lds + 73728 + (n & 1) * 32768 + (wid * 32 + l31) * 2 + hh * (8 * 512));
;     ...
; #pragma unroll
;         for (int t = 0; t < 8; ++t)
; #pragma unroll
;             for (int s2 = 0; s2 < 2; ++s2) {
;                 const bf16x8 sb = packB(S[t], s2);
; #pragma unroll
;                 for (int rt = 0; rt < 2; ++rt) O[rt] = MFMA32(LDSV((rt * 16 + 2 * t + s2) * 1024), sb, O[rt]);
;                 if (s2 == 1 && (t & 1)) __builtin_amdgcn_sched_barrier(0);
;             }
.LBB0_1376:
	v_lshl_add_u64 v[188:189], s[78:79], 0, v[176:177]
	v_lshl_add_u64 v[130:131], v[188:189], 0, s[8:9]
	s_add_i32 m0, s55, 0xa000
	v_lshl_add_u64 v[190:191], s[78:79], 0, v[178:179]
	global_load_lds_dwordx4 v[130:131], off
	v_lshl_add_u64 v[130:131], v[190:191], 0, s[8:9]
	s_add_i32 m0, s55, 0xc000
	v_lshl_add_u64 v[192:193], s[78:79], 0, v[180:181]
	global_load_lds_dwordx4 v[130:131], off
	v_lshl_add_u64 v[130:131], v[192:193], 0, s[8:9]
	s_add_i32 m0, s55, 0xe000
	v_lshl_add_u64 v[194:195], s[78:79], 0, v[182:183]
	s_add_i32 s23, s22, 0
	global_load_lds_dwordx4 v[130:131], off
	v_lshl_add_u64 v[130:131], v[194:195], 0, s[8:9]
	s_add_i32 m0, s23, 0xa000
	v_cvt_pk_bf16_f32 v134, v114, v115
	global_load_lds_dwordx4 v[130:131], off
	ds_read_b128 v[130:133], v204
	ds_read_b128 v[214:217], v204 offset:1024
	v_cvt_pk_bf16_f32 v135, v116, v117
	v_cvt_pk_bf16_f32 v136, v118, v119
	v_cvt_pk_bf16_f32 v137, v120, v121
	v_cvt_pk_bf16_f32 v222, v122, v123
	v_cvt_pk_bf16_f32 v223, v124, v125
	s_waitcnt lgkmcnt(0)
	v_mfma_f32_32x32x16_bf16 v[146:161], v[130:133], v[134:137], 0
	ds_read_b128 v[130:133], v204 offset:16384
	ds_read_b128 v[218:221], v204 offset:17408
	v_cvt_pk_bf16_f32 v224, v126, v127
	v_cvt_pk_bf16_f32 v225, v128, v129
	s_add_i32 s23, s21, 0xffff8000
	s_and_b32 s23, s23, 0x8000
	s_waitcnt lgkmcnt(0)
	v_mfma_f32_32x32x16_bf16 v[130:145], v[130:133], v[134:137], 0
	v_mfma_f32_32x32x16_bf16 v[146:161], v[214:217], v[222:225], v[146:161]
	ds_read_b128 v[214:217], v204 offset:2048
	v_mfma_f32_32x32x16_bf16 v[130:145], v[218:221], v[222:225], v[130:145]
	v_cvt_pk_bf16_f32 v218, v98, v99
	v_cvt_pk_bf16_f32 v219, v100, v101
	v_cvt_pk_bf16_f32 v220, v102, v103
	v_cvt_pk_bf16_f32 v221, v104, v105
	ds_read_b128 v[222:225], v204 offset:3072
	s_waitcnt lgkmcnt(0)
	v_mfma_f32_32x32x16_bf16 v[146:161], v[214:217], v[218:221], v[146:161]
	ds_read_b128 v[214:217], v204 offset:18432
	ds_read_b128 v[226:229], v204 offset:19456
	s_waitcnt lgkmcnt(0)
	v_mfma_f32_32x32x16_bf16 v[130:145], v[214:217], v[218:221], v[130:145]
	v_cvt_pk_bf16_f32 v214, v106, v107
	v_cvt_pk_bf16_f32 v215, v108, v109
	v_cvt_pk_bf16_f32 v216, v110, v111
	v_cvt_pk_bf16_f32 v217, v112, v113
	s_nop 1
	v_mfma_f32_32x32x16_bf16 v[146:161], v[222:225], v[214:217], v[146:161]
	v_mfma_f32_32x32x16_bf16 v[130:145], v[226:229], v[214:217], v[130:145]
	ds_read_b128 v[214:217], v204 offset:4096
	ds_read_b128 v[222:225], v204 offset:5120
	v_cvt_pk_bf16_f32 v218, v82, v83
	v_cvt_pk_bf16_f32 v219, v84, v85
	v_cvt_pk_bf16_f32 v220, v86, v87
	v_cvt_pk_bf16_f32 v221, v88, v89
	s_waitcnt lgkmcnt(0)
	s_nop 0
	v_mfma_f32_32x32x16_bf16 v[146:161], v[214:217], v[218:221], v[146:161]
	ds_read_b128 v[214:217], v204 offset:20480
	ds_read_b128 v[226:229], v204 offset:21504
	s_waitcnt lgkmcnt(0)
	v_mfma_f32_32x32x16_bf16 v[130:145], v[214:217], v[218:221], v[130:145]
	v_cvt_pk_bf16_f32 v214, v90, v91
	v_cvt_pk_bf16_f32 v215, v92, v93
	v_cvt_pk_bf16_f32 v216, v94, v95
	v_cvt_pk_bf16_f32 v217, v96, v97
	v_cvt_pk_bf16_f32 v218, v50, v51
	v_cvt_pk_bf16_f32 v219, v52, v53
	v_cvt_pk_bf16_f32 v220, v54, v55
	v_mfma_f32_32x32x16_bf16 v[146:161], v[222:225], v[214:217], v[146:161]
	v_cvt_pk_bf16_f32 v221, v56, v57
	ds_read_b128 v[222:225], v204 offset:7168
	v_mfma_f32_32x32x16_bf16 v[130:145], v[226:229], v[214:217], v[130:145]
	ds_read_b128 v[214:217], v204 offset:6144
	s_waitcnt lgkmcnt(0)
	v_mfma_f32_32x32x16_bf16 v[146:161], v[214:217], v[218:221], v[146:161]
	ds_read_b128 v[214:217], v204 offset:22528
	ds_read_b128 v[226:229], v204 offset:23552
	s_waitcnt lgkmcnt(0)
	v_mfma_f32_32x32x16_bf16 v[130:145], v[214:217], v[218:221], v[130:145]
	v_cvt_pk_bf16_f32 v214, v58, v59
	v_cvt_pk_bf16_f32 v215, v60, v61
	v_cvt_pk_bf16_f32 v216, v62, v63
	v_cvt_pk_bf16_f32 v217, v64, v65
	s_nop 1
	v_mfma_f32_32x32x16_bf16 v[146:161], v[222:225], v[214:217], v[146:161]
	v_mfma_f32_32x32x16_bf16 v[130:145], v[226:229], v[214:217], v[130:145]
	ds_read_b128 v[214:217], v204 offset:8192
	ds_read_b128 v[222:225], v204 offset:9216
	v_cvt_pk_bf16_f32 v218, v66, v67
	v_cvt_pk_bf16_f32 v219, v68, v69
	v_cvt_pk_bf16_f32 v220, v70, v71
	v_cvt_pk_bf16_f32 v221, v72, v73
	s_waitcnt lgkmcnt(0)
	s_nop 0
	v_mfma_f32_32x32x16_bf16 v[146:161], v[214:217], v[218:221], v[146:161]
	ds_read_b128 v[214:217], v204 offset:24576
	ds_read_b128 v[226:229], v204 offset:25600
	s_waitcnt lgkmcnt(0)
	v_mfma_f32_32x32x16_bf16 v[130:145], v[214:217], v[218:221], v[130:145]
	v_cvt_pk_bf16_f32 v214, v74, v75
	v_cvt_pk_bf16_f32 v215, v76, v77
	v_cvt_pk_bf16_f32 v216, v78, v79
	v_cvt_pk_bf16_f32 v217, v80, v81
	v_cvt_pk_bf16_f32 v218, v34, v35
	v_cvt_pk_bf16_f32 v219, v36, v37
	v_cvt_pk_bf16_f32 v220, v38, v39
	v_mfma_f32_32x32x16_bf16 v[146:161], v[222:225], v[214:217], v[146:161]
	v_cvt_pk_bf16_f32 v221, v40, v41
	ds_read_b128 v[222:225], v204 offset:11264
	v_mfma_f32_32x32x16_bf16 v[130:145], v[226:229], v[214:217], v[130:145]
	ds_read_b128 v[214:217], v204 offset:10240
	s_waitcnt lgkmcnt(0)
	v_mfma_f32_32x32x16_bf16 v[146:161], v[214:217], v[218:221], v[146:161]
	ds_read_b128 v[214:217], v204 offset:26624
	ds_read_b128 v[226:229], v204 offset:27648
	s_waitcnt lgkmcnt(0)
	v_mfma_f32_32x32x16_bf16 v[130:145], v[214:217], v[218:221], v[130:145]
	v_cvt_pk_bf16_f32 v214, v42, v43
	v_cvt_pk_bf16_f32 v215, v44, v45
	v_cvt_pk_bf16_f32 v216, v46, v47
	v_cvt_pk_bf16_f32 v217, v48, v49
	s_nop 1
	v_mfma_f32_32x32x16_bf16 v[146:161], v[222:225], v[214:217], v[146:161]
	v_mfma_f32_32x32x16_bf16 v[130:145], v[226:229], v[214:217], v[130:145]
	ds_read_b128 v[214:217], v204 offset:12288
	ds_read_b128 v[222:225], v204 offset:13312
	v_cvt_pk_bf16_f32 v218, v18, v19
	v_cvt_pk_bf16_f32 v219, v20, v21
	v_cvt_pk_bf16_f32 v220, v22, v23
	v_cvt_pk_bf16_f32 v221, v24, v25
	s_waitcnt lgkmcnt(0)
; #define LAS __attribute__((address_space(3)))
; #define MFMA32(a, b, c) __builtin_amdgcn_mfma_f32_32x32x16_bf16((a), (b), (c), 0, 0, 0)
; DI void ret_scan_prompt(const Params& p, int item, unsigned char* smem) {
;     ...
;         const LAS unsigned short* vcol = (const LAS unsigned short*)(lds + 73728 + (n & 1) * 32768 + (wid * 32 + l31) * 2 + hh * (8 * 512));
;     ...
; #pragma unroll
;         for (int t = 0; t < 8; ++t)
; #pragma unroll
;             for (int s2 = 0; s2 < 2; ++s2) {
;                 const bf16x8 sb = packB(S[t], s2);
; #pragma unroll
;                 for (int rt = 0; rt < 2; ++rt) O[rt] = MFMA32(LDSV((rt * 16 + 2 * t + s2) * 1024), sb, O[rt]);
;                 if (s2 == 1 && (t & 1)) __builtin_amdgcn_sched_barrier(0);
;             }
; #pragma unroll
;         for (int kc = 0; kc < 4; ++kc) { const bf16x8 vb = RET_VFRAG(kc);
; #pragma unroll
;             for (int rt = (kc >> 1); rt < 2; ++rt) O[rt] = MFMA32(LDSV(32768 + (rt * 4 + kc) * 1024), vb, O[rt]); }
	s_nop 0
	v_mfma_f32_32x32x16_bf16 v[146:161], v[214:217], v[218:221], v[146:161]
	ds_read_b128 v[214:217], v204 offset:28672
	ds_read_b128 v[226:229], v204 offset:29696
	s_waitcnt lgkmcnt(0)
	v_mfma_f32_32x32x16_bf16 v[130:145], v[214:217], v[218:221], v[130:145]
	v_cvt_pk_bf16_f32 v214, v26, v27
	v_cvt_pk_bf16_f32 v215, v28, v29
	v_cvt_pk_bf16_f32 v216, v30, v31
	v_cvt_pk_bf16_f32 v217, v32, v33
	v_cvt_pk_bf16_f32 v218, v2, v3
	v_cvt_pk_bf16_f32 v219, v4, v5
	v_cvt_pk_bf16_f32 v220, v6, v7
	v_mfma_f32_32x32x16_bf16 v[146:161], v[222:225], v[214:217], v[146:161]
	v_cvt_pk_bf16_f32 v221, v8, v9
	ds_read_b128 v[222:225], v204 offset:15360
	v_mfma_f32_32x32x16_bf16 v[130:145], v[226:229], v[214:217], v[130:145]
	ds_read_b128 v[214:217], v204 offset:14336
	s_waitcnt lgkmcnt(0)
	v_mfma_f32_32x32x16_bf16 v[146:161], v[214:217], v[218:221], v[146:161]
	ds_read_b128 v[214:217], v204 offset:30720
	ds_read_b128 v[226:229], v204 offset:31744
	s_waitcnt lgkmcnt(0)
	v_mfma_f32_32x32x16_bf16 v[130:145], v[214:217], v[218:221], v[130:145]
	v_cvt_pk_bf16_f32 v214, v10, v11
	v_cvt_pk_bf16_f32 v215, v12, v13
	v_cvt_pk_bf16_f32 v216, v14, v15
	v_cvt_pk_bf16_f32 v217, v16, v17
	s_nop 1
	v_mfma_f32_32x32x16_bf16 v[146:161], v[222:225], v[214:217], v[146:161]
	v_mfma_f32_32x32x16_bf16 v[130:145], v[226:229], v[214:217], v[130:145]
	v_add_u32_e32 v168, s23, v205
	ds_read_b128 v[214:217], v204 offset:32768
	ds_read_u16 v171, v168 offset:512
	ds_read_u16 v221, v168 offset:3072
	ds_read_u16 v220, v168 offset:2048
	ds_read_u16 v219, v168 offset:1024
	ds_read_u16 v218, v168
	ds_read_u16 v222, v168 offset:1536
	ds_read_u16 v223, v168 offset:2560
	ds_read_u16 v224, v168 offset:3584
	s_mov_b32 s23, 0x3c82000
	s_waitcnt lgkmcnt(0)
	v_lshl_or_b32 v218, v171, 16, v218
	v_lshl_or_b32 v219, v222, 16, v219
	v_lshl_or_b32 v220, v223, 16, v220
	v_lshl_or_b32 v221, v224, 16, v221
	ds_read_b128 v[222:225], v204 offset:33792
	s_cmp_eq_u32 s21, 0x100000
	v_mfma_f32_32x32x16_bf16 v[146:161], v[214:217], v[218:221], v[146:161]
	ds_read_b128 v[214:217], v204 offset:36864
	ds_read_b128 v[226:229], v204 offset:37888
	s_waitcnt lgkmcnt(0)
	v_mfma_f32_32x32x16_bf16 v[130:145], v[214:217], v[218:221], v[130:145]
	ds_read_u16 v171, v168 offset:8704
	ds_read_u16 v217, v168 offset:11264
	ds_read_u16 v216, v168 offset:10240
	ds_read_u16 v215, v168 offset:9216
	ds_read_u16 v214, v168 offset:8192
	ds_read_u16 v218, v168 offset:9728
	ds_read_u16 v219, v168 offset:10752
	ds_read_u16 v220, v168 offset:11776
	s_waitcnt lgkmcnt(0)
	v_lshl_or_b32 v214, v171, 16, v214
	v_lshl_or_b32 v215, v218, 16, v215
	v_lshl_or_b32 v216, v219, 16, v216
	v_lshl_or_b32 v217, v220, 16, v217
	s_nop 1
	v_mfma_f32_32x32x16_bf16 v[130:145], v[226:229], v[214:217], v[130:145]
	v_mfma_f32_32x32x16_bf16 v[146:161], v[222:225], v[214:217], v[146:161]
	ds_read_b128 v[214:217], v204 offset:38912
	ds_read_u16 v171, v168 offset:16896
	ds_read_u16 v221, v168 offset:19456
	ds_read_u16 v220, v168 offset:18432
	ds_read_u16 v219, v168 offset:17408
	ds_read_u16 v218, v168 offset:16384
	ds_read_u16 v222, v168 offset:17920
	ds_read_u16 v223, v168 offset:18944
	ds_read_u16 v224, v168 offset:19968
	s_waitcnt lgkmcnt(0)
	v_lshl_or_b32 v218, v171, 16, v218
	v_lshl_or_b32 v219, v222, 16, v219
	v_lshl_or_b32 v220, v223, 16, v220
	v_lshl_or_b32 v221, v224, 16, v221
	ds_read_b128 v[222:225], v204 offset:39936
	v_cvt_pk_bf16_f32 v146, v146, s0
	v_mfma_f32_32x32x16_bf16 v[130:145], v[214:217], v[218:221], v[130:145]
	ds_read_u16 v171, v168 offset:25088
	ds_read_u16 v217, v168 offset:27648
	ds_read_u16 v216, v168 offset:26624
	ds_read_u16 v215, v168 offset:25600
	ds_read_u16 v214, v168 offset:24576
	ds_read_u16 v218, v168 offset:26112
	ds_read_u16 v219, v168 offset:27136
	ds_read_u16 v220, v168 offset:28160
	v_cvt_pk_bf16_f32 v148, v148, s0
	s_waitcnt lgkmcnt(0)
; DI bf16_t f2bf(float a) { return (bf16_t)(pk_bf16(a, 0.f) & 0xffffu); }
; DI int crow(int i, int hh) { return (i & 3) + 8 * (i >> 2) + 4 * hh; }
; DI void lds_barrier() { asm volatile("s_waitcnt lgkmcnt(0)" ::: "memory"); __builtin_amdgcn_s_barrier(); asm volatile("" ::: "memory"); }
; #define RET_DMA_A(n) do { const unsigned char* g_ = gblk + (size_t)(n) * ROP_STRIDE; RET_CP(0, 0, 4); RET_CP(65536, 32768, 1); RET_DMA_V(n); } while (0)
; DI void ret_scan_prompt(const Params& p, int item, unsigned char* smem) {
;     ...
;         const size_t tok0 = (size_t)b * 2048 + n * 64;
; #pragma unroll
;         for (int rt = 0; rt < 2; ++rt)
; #pragma unroll
;             for (int i = 0; i < 16; ++i) oraw[(tok0 + 32 * rt + crow(i, hh)) * 2048 + h * 512 + 32 * s + l31] = f2bf(O[rt][i]);
;         asm volatile("s_waitcnt vmcnt(0)" ::: "memory"); lds_barrier();
;         if (n + 1 < 32) RET_DMA_A(n + 1);
	v_lshl_or_b32 v214, v171, 16, v214
	v_lshl_or_b32 v215, v218, 16, v215
	v_lshl_or_b32 v216, v219, 16, v216
	v_lshl_or_b32 v217, v220, 16, v217
	v_cvt_pk_bf16_f32 v171, v147, s0
	v_cvt_pk_bf16_f32 v150, v150, s0
	v_mfma_f32_32x32x16_bf16 v[130:145], v[222:225], v[214:217], v[130:145]
	v_lshl_add_u64 v[214:215], s[78:79], 0, v[186:187]
	global_store_short v[214:215], v146, off
	v_lshl_add_u64 v[146:147], s[78:79], 0, v[184:185]
	v_add_co_u32_e32 v214, vcc, s23, v146
	s_mov_b32 s23, 0x3c83000
	s_nop 0
	v_addc_co_u32_e32 v215, vcc, 0, v147, vcc
	global_store_short v[214:215], v148, off
	v_add_co_u32_e32 v148, vcc, s23, v146
	global_store_short v[214:215], v171, off offset:-4096
	v_cvt_pk_bf16_f32 v171, v149, s0
	v_addc_co_u32_e32 v149, vcc, 0, v147, vcc
	s_mov_b32 s23, 0x3c89000
	global_store_short v[148:149], v171, off
	v_add_co_u32_e32 v148, vcc, s23, v146
	s_mov_b32 s23, 0x3c8b000
	s_nop 0
	v_addc_co_u32_e32 v149, vcc, 0, v147, vcc
	global_store_short v[148:149], v150, off offset:-4096
	v_cvt_pk_bf16_f32 v150, v151, s0
	global_store_short v[148:149], v150, off
	v_add_co_u32_e32 v148, vcc, s23, v146
	v_cvt_pk_bf16_f32 v150, v152, s0
	s_nop 0
	v_addc_co_u32_e32 v149, vcc, 0, v147, vcc
	global_store_short v[148:149], v150, off offset:-4096
	v_cvt_pk_bf16_f32 v150, v153, s0
	s_mov_b32 s23, 0x3c91000
	global_store_short v[148:149], v150, off
	v_add_co_u32_e32 v148, vcc, s23, v146
	v_cvt_pk_bf16_f32 v150, v154, s0
	s_nop 0
	v_addc_co_u32_e32 v149, vcc, 0, v147, vcc
	global_store_short v[148:149], v150, off offset:-4096
	v_cvt_pk_bf16_f32 v150, v155, s0
	s_mov_b32 s23, 0x3c93000
	global_store_short v[148:149], v150, off
	v_add_co_u32_e32 v148, vcc, s23, v146
	v_cvt_pk_bf16_f32 v150, v156, s0
	s_nop 0
	v_addc_co_u32_e32 v149, vcc, 0, v147, vcc
	global_store_short v[148:149], v150, off offset:-4096
	v_cvt_pk_bf16_f32 v150, v157, s0
	s_mov_b32 s23, 0x3c99000
	global_store_short v[148:149], v150, off
	v_add_co_u32_e32 v148, vcc, s23, v146
	v_cvt_pk_bf16_f32 v150, v158, s0
	s_nop 0
	v_addc_co_u32_e32 v149, vcc, 0, v147, vcc
	global_store_short v[148:149], v150, off offset:-4096
	v_cvt_pk_bf16_f32 v150, v159, s0
	s_mov_b32 s23, 0x3c9b000
	global_store_short v[148:149], v150, off
	v_add_co_u32_e32 v148, vcc, s23, v146
	v_cvt_pk_bf16_f32 v150, v160, s0
	s_nop 0
	v_addc_co_u32_e32 v149, vcc, 0, v147, vcc
	global_store_short v[148:149], v150, off offset:-4096
	v_cvt_pk_bf16_f32 v150, v161, s0
	s_mov_b32 s23, 0x3ca1000
	global_store_short v[148:149], v150, off
	v_add_co_u32_e32 v148, vcc, s23, v146
	v_cvt_pk_bf16_f32 v130, v130, s0
	s_nop 0
	v_addc_co_u32_e32 v149, vcc, 0, v147, vcc
	global_store_short v[148:149], v130, off offset:-4096
	v_cvt_pk_bf16_f32 v130, v131, s0
	s_mov_b32 s23, 0x3ca3000
	global_store_short v[148:149], v130, off
	v_add_co_u32_e32 v130, vcc, s23, v146
	v_cvt_pk_bf16_f32 v132, v132, s0
	s_nop 0
	v_addc_co_u32_e32 v131, vcc, 0, v147, vcc
	global_store_short v[130:131], v132, off offset:-4096
	v_cvt_pk_bf16_f32 v132, v133, s0
	s_mov_b32 s23, 0x3ca9000
	global_store_short v[130:131], v132, off
	v_add_co_u32_e32 v130, vcc, s23, v146
	v_cvt_pk_bf16_f32 v132, v134, s0
	s_nop 0
	v_addc_co_u32_e32 v131, vcc, 0, v147, vcc
	global_store_short v[130:131], v132, off offset:-4096
	v_cvt_pk_bf16_f32 v132, v135, s0
	s_mov_b32 s23, 0x3cab000
	global_store_short v[130:131], v132, off
	v_add_co_u32_e32 v130, vcc, s23, v146
	v_cvt_pk_bf16_f32 v132, v136, s0
	s_nop 0
	v_addc_co_u32_e32 v131, vcc, 0, v147, vcc
	global_store_short v[130:131], v132, off offset:-4096
	v_cvt_pk_bf16_f32 v132, v137, s0
	s_mov_b32 s23, 0x3cb1000
	global_store_short v[130:131], v132, off
	v_add_co_u32_e32 v130, vcc, s23, v146
	v_cvt_pk_bf16_f32 v132, v138, s0
	s_nop 0
	v_addc_co_u32_e32 v131, vcc, 0, v147, vcc
	global_store_short v[130:131], v132, off offset:-4096
	v_cvt_pk_bf16_f32 v132, v139, s0
	s_mov_b32 s23, 0x3cb3000
	global_store_short v[130:131], v132, off
	v_add_co_u32_e32 v130, vcc, s23, v146
	v_cvt_pk_bf16_f32 v132, v140, s0
	s_nop 0
	v_addc_co_u32_e32 v131, vcc, 0, v147, vcc
	global_store_short v[130:131], v132, off offset:-4096
	v_cvt_pk_bf16_f32 v132, v141, s0
	s_mov_b32 s23, 0x3cb9000
	global_store_short v[130:131], v132, off
	v_add_co_u32_e32 v130, vcc, s23, v146
	v_cvt_pk_bf16_f32 v132, v142, s0
	s_nop 0
	v_addc_co_u32_e32 v131, vcc, 0, v147, vcc
	global_store_short v[130:131], v132, off offset:-4096
	v_cvt_pk_bf16_f32 v132, v143, s0
	global_store_short v[130:131], v132, off
	v_add_co_u32_e32 v130, vcc, 0x3cba000, v146
	v_cvt_pk_bf16_f32 v132, v144, s0
	s_nop 0
	v_addc_co_u32_e32 v131, vcc, 0, v147, vcc
	global_store_short v[130:131], v132, off
	v_add_co_u32_e32 v130, vcc, 0x3cbb000, v146
	v_cvt_pk_bf16_f32 v132, v145, s0
	s_nop 0
	v_addc_co_u32_e32 v131, vcc, 0, v147, vcc
	global_store_short v[130:131], v132, off
	s_waitcnt vmcnt(32)
	s_waitcnt lgkmcnt(0)
	s_barrier
	s_cbranch_scc1 .LBB0_1375
	s_mov_b32 m0, s55
	v_lshl_add_u64 v[130:131], v[188:189], 0, s[10:11]
	global_load_lds_dwordx4 v[130:131], off
	v_lshl_add_u64 v[130:131], v[190:191], 0, s[10:11]
	s_mov_b32 m0, s58
	s_mul_hi_i32 s35, s69, 0x1800
	s_mul_i32 s34, s69, 0x1800
	global_load_lds_dwordx4 v[130:131], off
	v_lshl_add_u64 v[130:131], v[192:193], 0, s[10:11]
	s_mov_b32 m0, s59
	s_or_b64 s[34:35], s[34:35], s[0:1]
	global_load_lds_dwordx4 v[130:131], off
	v_lshl_add_u64 v[130:131], v[194:195], 0, s[10:11]
	s_mov_b32 m0, s62
	s_lshl_b64 s[34:35], s[34:35], 1
	s_and_b32 s23, s21, 0x8000
	global_load_lds_dwordx4 v[130:131], off
	v_lshl_add_u64 v[130:131], v[188:189], 0, s[12:13]
	s_mov_b32 m0, s63
	s_bitset1_b32 s34, 12
	s_add_i32 s23, s23, 0
	global_load_lds_dwordx4 v[130:131], off
	v_lshl_add_u64 v[130:131], v[172:173], 0, s[34:35]
	s_add_i32 s23, s23, 0x12000
	v_lshl_add_u64 v[132:133], v[130:131], 0, s[24:25]
	s_add_i32 m0, s23, s20
	s_nop 0
	global_load_lds_dwordx4 v[132:133], off
	v_lshl_add_u64 v[132:133], v[130:131], 0, s[26:27]
	s_add_i32 m0, s23, s65
	s_nop 0
	global_load_lds_dwordx4 v[132:133], off
	v_lshl_add_u64 v[132:133], v[130:131], 0, s[28:29]
	s_add_i32 m0, s23, s66
	v_lshl_add_u64 v[130:131], v[130:131], 0, s[30:31]
	global_load_lds_dwordx4 v[132:133], off
	s_add_i32 m0, s23, s67
	s_nop 0
	global_load_lds_dwordx4 v[130:131], off
	s_branch .LBB0_1375

; DI float bflo(unsigned u) { return __uint_as_float(u << 16); }
; DI float bfhi(unsigned u) { return __uint_as_float(u & 0xffff0000u); }
; DI void phase_ret_gate(const Params& p) {
;     const int lane = threadIdx.x & 63, gw = blockIdx.x * 8 + (threadIdx.x >> 6), nw = gridDim.x * 8;
;     const bf16_t* oraw = (const bf16_t*)(p.ws + WS_ORAW); const bf16_t* P1 = (const bf16_t*)(p.ws + WS_P1); bf16_t* og = (bf16_t*)(p.ws + WS_OG);
;     for (int tok = gw; tok < T_TOK; tok += nw) {
;         float o[32]; float ss = 0.f;
; #pragma unroll
;         for (int q = 0; q < 4; ++q) { const u32x4 a = *(const u32x4*)(oraw + (size_t)tok * 2048 + 32 * lane + 8 * q); const unsigned au[4] = {a.x, a.y, a.z, a.w};
; #pragma unroll
;             for (int i = 0; i < 4; ++i) { o[8 * q + 2 * i] = bflo(au[i]); o[8 * q + 2 * i + 1] = bfhi(au[i]); ss += o[8 * q + 2 * i] * o[8 * q + 2 * i] + o[8 * q + 2 * i + 1] * o[8 * q + 2 * i + 1]; } }
;         ss = row16_sum(ss);
;         const float rstd = rsqrtf(ss * (1.f / 512.f) + 1e-6f);
;         const float* wn = p.onorm_b + 32 * lane;
; #pragma unroll
;         for (int q = 0; q < 4; ++q) { const u32x4 g = *(const u32x4*)(P1 + (size_t)tok * LDP1 + 4096 + 32 * lane + 8 * q); const unsigned gu[4] = {g.x, g.y, g.z, g.w}; unsigned r[4];
.LBB0_1446:
	s_cmp_lt_i32 s80, 11
	s_cselect_b64 s[4:5], -1, 0
	s_and_b64 s[0:1], s[4:5], s[0:1]
	s_and_b64 s[0:1], s[44:45], s[0:1]
	s_and_saveexec_b64 s[6:7], s[0:1]
	s_cbranch_execz .LBB0_1449
	v_readlane_b32 s14, v238, 12
	v_readlane_b32 s15, v238, 13
	v_lshlrev_b32_e32 v2, 6, v196
	v_lshlrev_b32_e32 v3, 7, v196
	s_add_u32 s10, s78, 0x3c80000
	s_addc_u32 s11, s79, 0
	s_add_u32 s12, s78, 0x1d482000
	s_addc_u32 s13, s79, 0
	s_add_u32 s16, s78, 0x8080000
	s_addc_u32 s17, s79, 0
	global_load_dwordx4 v[16:19], v3, s[14:15]
	global_load_dwordx4 v[20:23], v3, s[14:15] offset:16
	global_load_dwordx4 v[24:27], v3, s[14:15] offset:32
	global_load_dwordx4 v[28:31], v3, s[14:15] offset:48
	global_load_dwordx4 v[32:35], v3, s[14:15] offset:64
	global_load_dwordx4 v[36:39], v3, s[14:15] offset:80
	global_load_dwordx4 v[40:43], v3, s[14:15] offset:96
	global_load_dwordx4 v[44:47], v3, s[14:15] offset:112
	v_readfirstlane_b32 s8, v162
	s_mov_b32 s23, 0
	v_mov_b32_e32 v15, 0x358637bd
	s_lshl_b32 s9, s8, 12
	v_add_u32_e32 v4, s9, v2
	s_mul_i32 s9, s8, 0x3000
	v_add_u32_e32 v5, s9, v2
	global_load_dwordx4 v[48:51], v4, s[10:11]
	global_load_dwordx4 v[52:55], v4, s[10:11] offset:16
	global_load_dwordx4 v[56:59], v4, s[10:11] offset:32
	global_load_dwordx4 v[60:63], v4, s[10:11] offset:48
	global_load_dwordx4 v[64:67], v5, s[12:13]
	global_load_dwordx4 v[68:71], v5, s[12:13] offset:16
	global_load_dwordx4 v[72:75], v5, s[12:13] offset:32
	global_load_dwordx4 v[76:79], v5, s[12:13] offset:48
.Lg10_a:
	s_add_u32 s22, s8, s46
	s_cmp_lt_u32 s22, 0x4400
	s_cbranch_scc0 .Lg10_a_nonext
	s_lshl_b32 s9, s22, 12
	v_add_u32_e32 v4, s9, v2
	s_mul_i32 s9, s22, 0x3000
	v_add_u32_e32 v5, s9, v2
	global_load_dwordx4 v[80:83], v4, s[10:11]
	global_load_dwordx4 v[84:87], v4, s[10:11] offset:16
	global_load_dwordx4 v[88:91], v4, s[10:11] offset:32
	global_load_dwordx4 v[92:95], v4, s[10:11] offset:48
	global_load_dwordx4 v[96:99], v5, s[12:13]
	global_load_dwordx4 v[100:103], v5, s[12:13] offset:16
	global_load_dwordx4 v[104:107], v5, s[12:13] offset:32
	global_load_dwordx4 v[108:111], v5, s[12:13] offset:48
	s_cmp_eq_u32 s23, 0
	s_cbranch_scc1 .Lg10_a_w8
	s_waitcnt vmcnt(12)
	s_branch .Lg10_a_have
.Lg10_a_w8:
	s_waitcnt vmcnt(8)
	s_branch .Lg10_a_have

; DI unsigned pk_bf16(float a, float b) { f32x2 v = {a, b}; bf2_t r = __builtin_convertvector(v, bf2_t); return __builtin_bit_cast(unsigned, r); }
; DI float bflo(unsigned u) { return __uint_as_float(u << 16); }
; DI float bfhi(unsigned u) { return __uint_as_float(u & 0xffff0000u); }
; DI float silu_f(float x) { return x * __builtin_amdgcn_rcpf(1.f + __expf(-x)); }
; DI void phase_ret_gate(const Params& p) {
;     ...
;     for (int tok = gw; tok < T_TOK; tok += nw) {
;         float o[32]; float ss = 0.f;
; #pragma unroll
;         for (int q = 0; q < 4; ++q) { const u32x4 a = *(const u32x4*)(oraw + (size_t)tok * 2048 + 32 * lane + 8 * q); const unsigned au[4] = {a.x, a.y, a.z, a.w};
; #pragma unroll
;             for (int i = 0; i < 4; ++i) { o[8 * q + 2 * i] = bflo(au[i]); o[8 * q + 2 * i + 1] = bfhi(au[i]); ss += o[8 * q + 2 * i] * o[8 * q + 2 * i] + o[8 * q + 2 * i + 1] * o[8 * q + 2 * i + 1]; } }
;         ss = row16_sum(ss);
;         const float rstd = rsqrtf(ss * (1.f / 512.f) + 1e-6f);
;         const float* wn = p.onorm_b + 32 * lane;
; #pragma unroll
;         for (int q = 0; q < 4; ++q) { const u32x4 g = *(const u32x4*)(P1 + (size_t)tok * LDP1 + 4096 + 32 * lane + 8 * q); const unsigned gu[4] = {g.x, g.y, g.z, g.w}; unsigned r[4];
; #pragma unroll
;             for (int i = 0; i < 4; ++i) { const float v0 = o[8 * q + 2 * i] * rstd * wn[8 * q + 2 * i] * silu_f(bflo(gu[i])), v1 = o[8 * q + 2 * i + 1] * rstd * wn[8 * q + 2 * i + 1] * silu_f(bfhi(gu[i])); r[i] = pk_bf16(v0, v1); }
.Lg10_a_have:
	s_mov_b32 s23, 1
	v_lshlrev_b32_e32 v112, 16, v48
	v_and_b32_e32 v113, 0xffff0000, v48
	v_lshlrev_b32_e32 v114, 16, v49
	v_and_b32_e32 v115, 0xffff0000, v49
	v_lshlrev_b32_e32 v116, 16, v50
	v_and_b32_e32 v117, 0xffff0000, v50
	v_lshlrev_b32_e32 v118, 16, v51
	v_and_b32_e32 v119, 0xffff0000, v51
	v_lshlrev_b32_e32 v120, 16, v52
	v_and_b32_e32 v121, 0xffff0000, v52
	v_lshlrev_b32_e32 v122, 16, v53
	v_and_b32_e32 v123, 0xffff0000, v53
	v_lshlrev_b32_e32 v124, 16, v54
	v_and_b32_e32 v125, 0xffff0000, v54
	v_lshlrev_b32_e32 v126, 16, v55
	v_and_b32_e32 v127, 0xffff0000, v55
	v_lshlrev_b32_e32 v128, 16, v56
	v_and_b32_e32 v129, 0xffff0000, v56
	v_lshlrev_b32_e32 v130, 16, v57
	v_and_b32_e32 v131, 0xffff0000, v57
	v_lshlrev_b32_e32 v132, 16, v58
	v_and_b32_e32 v133, 0xffff0000, v58
	v_lshlrev_b32_e32 v134, 16, v59
	v_and_b32_e32 v135, 0xffff0000, v59
	v_lshlrev_b32_e32 v136, 16, v60
	v_and_b32_e32 v137, 0xffff0000, v60
	v_lshlrev_b32_e32 v138, 16, v61
	v_and_b32_e32 v139, 0xffff0000, v61
	v_lshlrev_b32_e32 v140, 16, v62
	v_and_b32_e32 v141, 0xffff0000, v62
	v_lshlrev_b32_e32 v142, 16, v63
	v_and_b32_e32 v143, 0xffff0000, v63
	v_mul_f32_e32 v144, v112, v112
	v_fmac_f32_e32 v144, v113, v113
	v_fmac_f32_e32 v144, v114, v114
	v_fmac_f32_e32 v144, v115, v115
	v_fmac_f32_e32 v144, v116, v116
	v_fmac_f32_e32 v144, v117, v117
	v_fmac_f32_e32 v144, v118, v118
	v_fmac_f32_e32 v144, v119, v119
	v_mul_f32_e32 v145, v120, v120
	v_fmac_f32_e32 v145, v121, v121
	v_fmac_f32_e32 v145, v122, v122
	v_fmac_f32_e32 v145, v123, v123
	v_fmac_f32_e32 v145, v124, v124
	v_fmac_f32_e32 v145, v125, v125
	v_fmac_f32_e32 v145, v126, v126
	v_fmac_f32_e32 v145, v127, v127
	v_mul_f32_e32 v146, v128, v128
	v_fmac_f32_e32 v146, v129, v129
	v_fmac_f32_e32 v146, v130, v130
	v_fmac_f32_e32 v146, v131, v131
	v_fmac_f32_e32 v146, v132, v132
	v_fmac_f32_e32 v146, v133, v133
	v_fmac_f32_e32 v146, v134, v134
	v_fmac_f32_e32 v146, v135, v135
	v_mul_f32_e32 v147, v136, v136
	v_fmac_f32_e32 v147, v137, v137
	v_fmac_f32_e32 v147, v138, v138
	v_fmac_f32_e32 v147, v139, v139
	v_fmac_f32_e32 v147, v140, v140
	v_fmac_f32_e32 v147, v141, v141
	v_fmac_f32_e32 v147, v142, v142
	v_fmac_f32_e32 v147, v143, v143
	v_add_f32_e32 v144, v144, v145
	v_add_f32_e32 v146, v146, v147
	v_add_f32_e32 v144, v144, v146
	v_lshlrev_b32_e32 v198, 16, v64
	v_and_b32_e32 v199, 0xffff0000, v64
	v_lshlrev_b32_e32 v200, 16, v65
	v_and_b32_e32 v201, 0xffff0000, v65
	v_lshlrev_b32_e32 v202, 16, v66
	v_and_b32_e32 v203, 0xffff0000, v66
	v_lshlrev_b32_e32 v204, 16, v67
	v_and_b32_e32 v205, 0xffff0000, v67
	v_lshlrev_b32_e32 v206, 16, v68
	v_and_b32_e32 v207, 0xffff0000, v68
	v_lshlrev_b32_e32 v208, 16, v69
	v_and_b32_e32 v209, 0xffff0000, v69
	v_lshlrev_b32_e32 v210, 16, v70
	v_and_b32_e32 v211, 0xffff0000, v70
	v_lshlrev_b32_e32 v212, 16, v71
	v_and_b32_e32 v213, 0xffff0000, v71
	v_lshlrev_b32_e32 v214, 16, v72
	v_and_b32_e32 v215, 0xffff0000, v72
	v_lshlrev_b32_e32 v216, 16, v73
	v_and_b32_e32 v217, 0xffff0000, v73
	v_lshlrev_b32_e32 v218, 16, v74
	v_and_b32_e32 v219, 0xffff0000, v74
	v_lshlrev_b32_e32 v220, 16, v75
	v_and_b32_e32 v221, 0xffff0000, v75
	v_lshlrev_b32_e32 v222, 16, v76
	v_and_b32_e32 v223, 0xffff0000, v76
	v_lshlrev_b32_e32 v224, 16, v77
	v_and_b32_e32 v225, 0xffff0000, v77
	v_lshlrev_b32_e32 v226, 16, v78
	v_and_b32_e32 v227, 0xffff0000, v78
	v_lshlrev_b32_e32 v228, 16, v79
	v_and_b32_e32 v229, 0xffff0000, v79
	s_nop 1
	v_add_f32_dpp v144, v144, v144 quad_perm:[1,0,3,2] row_mask:0xf bank_mask:0xf bound_ctrl:1
	s_nop 1
	v_add_f32_dpp v144, v144, v144 quad_perm:[2,3,0,1] row_mask:0xf bank_mask:0xf bound_ctrl:1
	s_nop 1
	v_add_f32_dpp v144, v144, v144 row_ror:4 row_mask:0xf bank_mask:0xf bound_ctrl:1
	s_nop 1
	v_add_f32_dpp v144, v144, v144 row_ror:8 row_mask:0xf bank_mask:0xf bound_ctrl:1
	v_fmamk_f32 v144, v144, 0x3b000000, v15
	v_rsq_f32_e32 v144, v144
	v_mul_f32_e32 v148, 0xbfb8aa3b, v198
	v_mul_f32_e32 v149, 0xbfb8aa3b, v199
	v_mul_f32_e32 v150, 0xbfb8aa3b, v200
	v_mul_f32_e32 v151, 0xbfb8aa3b, v201
	v_mul_f32_e32 v152, 0xbfb8aa3b, v202
	v_mul_f32_e32 v153, 0xbfb8aa3b, v203
	v_mul_f32_e32 v154, 0xbfb8aa3b, v204
	v_mul_f32_e32 v155, 0xbfb8aa3b, v205
	v_exp_f32_e32 v148, v148
	v_exp_f32_e32 v149, v149
	v_exp_f32_e32 v150, v150
	v_exp_f32_e32 v151, v151
	v_exp_f32_e32 v152, v152
	v_exp_f32_e32 v153, v153
	v_exp_f32_e32 v154, v154
	v_exp_f32_e32 v155, v155
	v_add_f32_e32 v148, 1.0, v148
	v_add_f32_e32 v149, 1.0, v149
	v_add_f32_e32 v150, 1.0, v150
	v_add_f32_e32 v151, 1.0, v151
	v_add_f32_e32 v152, 1.0, v152
	v_add_f32_e32 v153, 1.0, v153
	v_add_f32_e32 v154, 1.0, v154
	v_add_f32_e32 v155, 1.0, v155
	v_rcp_f32_e32 v148, v148
	v_rcp_f32_e32 v149, v149
	v_rcp_f32_e32 v150, v150
	v_rcp_f32_e32 v151, v151
	v_rcp_f32_e32 v152, v152
	v_rcp_f32_e32 v153, v153
	v_rcp_f32_e32 v154, v154
	v_rcp_f32_e32 v155, v155
	v_mul_f32_e32 v198, v148, v198
	v_mul_f32_e32 v199, v149, v199
	v_mul_f32_e32 v200, v150, v200
	v_mul_f32_e32 v201, v151, v201
	v_mul_f32_e32 v202, v152, v202
	v_mul_f32_e32 v203, v153, v203
	v_mul_f32_e32 v204, v154, v204
	v_mul_f32_e32 v205, v155, v205
	v_mul_f32_e32 v148, 0xbfb8aa3b, v206
	v_mul_f32_e32 v149, 0xbfb8aa3b, v207
	v_mul_f32_e32 v150, 0xbfb8aa3b, v208
	v_mul_f32_e32 v151, 0xbfb8aa3b, v209
	v_mul_f32_e32 v152, 0xbfb8aa3b, v210
	v_mul_f32_e32 v153, 0xbfb8aa3b, v211
	v_mul_f32_e32 v154, 0xbfb8aa3b, v212
	v_mul_f32_e32 v155, 0xbfb8aa3b, v213
	v_exp_f32_e32 v148, v148
	v_exp_f32_e32 v149, v149
	v_exp_f32_e32 v150, v150
	v_exp_f32_e32 v151, v151
	v_exp_f32_e32 v152, v152
	v_exp_f32_e32 v153, v153
	v_exp_f32_e32 v154, v154
	v_exp_f32_e32 v155, v155
	v_add_f32_e32 v148, 1.0, v148
; DI unsigned pk_bf16(float a, float b) { f32x2 v = {a, b}; bf2_t r = __builtin_convertvector(v, bf2_t); return __builtin_bit_cast(unsigned, r); }
; DI float bflo(unsigned u) { return __uint_as_float(u << 16); }
; DI float bfhi(unsigned u) { return __uint_as_float(u & 0xffff0000u); }
; DI float silu_f(float x) { return x * __builtin_amdgcn_rcpf(1.f + __expf(-x)); }
; DI void phase_ret_gate(const Params& p) {
;     ...
;         const float* wn = p.onorm_b + 32 * lane;
; #pragma unroll
;         for (int q = 0; q < 4; ++q) { const u32x4 g = *(const u32x4*)(P1 + (size_t)tok * LDP1 + 4096 + 32 * lane + 8 * q); const unsigned gu[4] = {g.x, g.y, g.z, g.w}; unsigned r[4];
; #pragma unroll
;             for (int i = 0; i < 4; ++i) { const float v0 = o[8 * q + 2 * i] * rstd * wn[8 * q + 2 * i] * silu_f(bflo(gu[i])), v1 = o[8 * q + 2 * i + 1] * rstd * wn[8 * q + 2 * i + 1] * silu_f(bfhi(gu[i])); r[i] = pk_bf16(v0, v1); }
;             *(u32x4*)(og + (size_t)tok * 2048 + 32 * lane + 8 * q) = (u32x4){r[0], r[1], r[2], r[3]}; }
	v_add_f32_e32 v149, 1.0, v149
	v_add_f32_e32 v150, 1.0, v150
	v_add_f32_e32 v151, 1.0, v151
	v_add_f32_e32 v152, 1.0, v152
	v_add_f32_e32 v153, 1.0, v153
	v_add_f32_e32 v154, 1.0, v154
	v_add_f32_e32 v155, 1.0, v155
	v_rcp_f32_e32 v148, v148
	v_rcp_f32_e32 v149, v149
	v_rcp_f32_e32 v150, v150
	v_rcp_f32_e32 v151, v151
	v_rcp_f32_e32 v152, v152
	v_rcp_f32_e32 v153, v153
	v_rcp_f32_e32 v154, v154
	v_rcp_f32_e32 v155, v155
	v_mul_f32_e32 v206, v148, v206
	v_mul_f32_e32 v207, v149, v207
	v_mul_f32_e32 v208, v150, v208
	v_mul_f32_e32 v209, v151, v209
	v_mul_f32_e32 v210, v152, v210
	v_mul_f32_e32 v211, v153, v211
	v_mul_f32_e32 v212, v154, v212
	v_mul_f32_e32 v213, v155, v213
	v_mul_f32_e32 v148, 0xbfb8aa3b, v214
	v_mul_f32_e32 v149, 0xbfb8aa3b, v215
	v_mul_f32_e32 v150, 0xbfb8aa3b, v216
	v_mul_f32_e32 v151, 0xbfb8aa3b, v217
	v_mul_f32_e32 v152, 0xbfb8aa3b, v218
	v_mul_f32_e32 v153, 0xbfb8aa3b, v219
	v_mul_f32_e32 v154, 0xbfb8aa3b, v220
	v_mul_f32_e32 v155, 0xbfb8aa3b, v221
	v_exp_f32_e32 v148, v148
	v_exp_f32_e32 v149, v149
	v_exp_f32_e32 v150, v150
	v_exp_f32_e32 v151, v151
	v_exp_f32_e32 v152, v152
	v_exp_f32_e32 v153, v153
	v_exp_f32_e32 v154, v154
	v_exp_f32_e32 v155, v155
	v_add_f32_e32 v148, 1.0, v148
	v_add_f32_e32 v149, 1.0, v149
	v_add_f32_e32 v150, 1.0, v150
	v_add_f32_e32 v151, 1.0, v151
	v_add_f32_e32 v152, 1.0, v152
	v_add_f32_e32 v153, 1.0, v153
	v_add_f32_e32 v154, 1.0, v154
	v_add_f32_e32 v155, 1.0, v155
	v_rcp_f32_e32 v148, v148
	v_rcp_f32_e32 v149, v149
	v_rcp_f32_e32 v150, v150
	v_rcp_f32_e32 v151, v151
	v_rcp_f32_e32 v152, v152
	v_rcp_f32_e32 v153, v153
	v_rcp_f32_e32 v154, v154
	v_rcp_f32_e32 v155, v155
	v_mul_f32_e32 v214, v148, v214
	v_mul_f32_e32 v215, v149, v215
	v_mul_f32_e32 v216, v150, v216
	v_mul_f32_e32 v217, v151, v217
	v_mul_f32_e32 v218, v152, v218
	v_mul_f32_e32 v219, v153, v219
	v_mul_f32_e32 v220, v154, v220
	v_mul_f32_e32 v221, v155, v221
	v_mul_f32_e32 v148, 0xbfb8aa3b, v222
	v_mul_f32_e32 v149, 0xbfb8aa3b, v223
	v_mul_f32_e32 v150, 0xbfb8aa3b, v224
	v_mul_f32_e32 v151, 0xbfb8aa3b, v225
	v_mul_f32_e32 v152, 0xbfb8aa3b, v226
	v_mul_f32_e32 v153, 0xbfb8aa3b, v227
	v_mul_f32_e32 v154, 0xbfb8aa3b, v228
	v_mul_f32_e32 v155, 0xbfb8aa3b, v229
	v_exp_f32_e32 v148, v148
	v_exp_f32_e32 v149, v149
	v_exp_f32_e32 v150, v150
	v_exp_f32_e32 v151, v151
	v_exp_f32_e32 v152, v152
	v_exp_f32_e32 v153, v153
	v_exp_f32_e32 v154, v154
	v_exp_f32_e32 v155, v155
	v_add_f32_e32 v148, 1.0, v148
	v_add_f32_e32 v149, 1.0, v149
	v_add_f32_e32 v150, 1.0, v150
	v_add_f32_e32 v151, 1.0, v151
	v_add_f32_e32 v152, 1.0, v152
	v_add_f32_e32 v153, 1.0, v153
	v_add_f32_e32 v154, 1.0, v154
	v_add_f32_e32 v155, 1.0, v155
	v_rcp_f32_e32 v148, v148
	v_rcp_f32_e32 v149, v149
	v_rcp_f32_e32 v150, v150
	v_rcp_f32_e32 v151, v151
	v_rcp_f32_e32 v152, v152
	v_rcp_f32_e32 v153, v153
	v_rcp_f32_e32 v154, v154
	v_rcp_f32_e32 v155, v155
	v_mul_f32_e32 v222, v148, v222
	v_mul_f32_e32 v223, v149, v223
	v_mul_f32_e32 v224, v150, v224
	v_mul_f32_e32 v225, v151, v225
	v_mul_f32_e32 v226, v152, v226
	v_mul_f32_e32 v227, v153, v227
	v_mul_f32_e32 v228, v154, v228
	v_mul_f32_e32 v229, v155, v229
	s_lshl_b32 s9, s8, 12
	s_add_u32 s20, s16, s9
	s_addc_u32 s21, s17, 0
	v_mul_f32_e32 v112, v144, v112
	v_mul_f32_e32 v113, v144, v113
	v_mul_f32_e32 v114, v144, v114
	v_mul_f32_e32 v115, v144, v115
	v_mul_f32_e32 v116, v144, v116
	v_mul_f32_e32 v117, v144, v117
	v_mul_f32_e32 v118, v144, v118
	v_mul_f32_e32 v119, v144, v119
	v_mul_f32_e32 v112, v16, v112
	v_mul_f32_e32 v113, v17, v113
	v_mul_f32_e32 v114, v18, v114
	v_mul_f32_e32 v115, v19, v115
	v_mul_f32_e32 v116, v20, v116
	v_mul_f32_e32 v117, v21, v117
	v_mul_f32_e32 v118, v22, v118
	v_mul_f32_e32 v119, v23, v119
	v_mul_f32_e32 v112, v198, v112
	v_mul_f32_e32 v113, v199, v113
	v_mul_f32_e32 v114, v200, v114
	v_mul_f32_e32 v115, v201, v115
	v_mul_f32_e32 v116, v202, v116
	v_mul_f32_e32 v117, v203, v117
	v_mul_f32_e32 v118, v204, v118
; DI unsigned pk_bf16(float a, float b) { f32x2 v = {a, b}; bf2_t r = __builtin_convertvector(v, bf2_t); return __builtin_bit_cast(unsigned, r); }
; DI float bflo(unsigned u) { return __uint_as_float(u << 16); }
; DI float bfhi(unsigned u) { return __uint_as_float(u & 0xffff0000u); }
; DI float silu_f(float x) { return x * __builtin_amdgcn_rcpf(1.f + __expf(-x)); }
; DI void phase_ret_gate(const Params& p) {
;     ...
;     for (int tok = gw; tok < T_TOK; tok += nw) {
;         float o[32]; float ss = 0.f;
; #pragma unroll
;         for (int q = 0; q < 4; ++q) { const u32x4 a = *(const u32x4*)(oraw + (size_t)tok * 2048 + 32 * lane + 8 * q); const unsigned au[4] = {a.x, a.y, a.z, a.w};
;     ...
;         for (int q = 0; q < 4; ++q) { const u32x4 g = *(const u32x4*)(P1 + (size_t)tok * LDP1 + 4096 + 32 * lane + 8 * q); const unsigned gu[4] = {g.x, g.y, g.z, g.w}; unsigned r[4];
; #pragma unroll
;             for (int i = 0; i < 4; ++i) { const float v0 = o[8 * q + 2 * i] * rstd * wn[8 * q + 2 * i] * silu_f(bflo(gu[i])), v1 = o[8 * q + 2 * i + 1] * rstd * wn[8 * q + 2 * i + 1] * silu_f(bfhi(gu[i])); r[i] = pk_bf16(v0, v1); }
;             *(u32x4*)(og + (size_t)tok * 2048 + 32 * lane + 8 * q) = (u32x4){r[0], r[1], r[2], r[3]}; }
;     }
	v_mul_f32_e32 v119, v205, v119
	v_cvt_pk_bf16_f32 v148, v112, v113
	v_cvt_pk_bf16_f32 v149, v114, v115
	v_cvt_pk_bf16_f32 v150, v116, v117
	v_cvt_pk_bf16_f32 v151, v118, v119
	s_nop 0
	global_store_dwordx4 v2, v[148:151], s[20:21]
	s_nop 1
	v_mul_f32_e32 v120, v144, v120
	v_mul_f32_e32 v121, v144, v121
	v_mul_f32_e32 v122, v144, v122
	v_mul_f32_e32 v123, v144, v123
	v_mul_f32_e32 v124, v144, v124
	v_mul_f32_e32 v125, v144, v125
	v_mul_f32_e32 v126, v144, v126
	v_mul_f32_e32 v127, v144, v127
	v_mul_f32_e32 v120, v24, v120
	v_mul_f32_e32 v121, v25, v121
	v_mul_f32_e32 v122, v26, v122
	v_mul_f32_e32 v123, v27, v123
	v_mul_f32_e32 v124, v28, v124
	v_mul_f32_e32 v125, v29, v125
	v_mul_f32_e32 v126, v30, v126
	v_mul_f32_e32 v127, v31, v127
	v_mul_f32_e32 v120, v206, v120
	v_mul_f32_e32 v121, v207, v121
	v_mul_f32_e32 v122, v208, v122
	v_mul_f32_e32 v123, v209, v123
	v_mul_f32_e32 v124, v210, v124
	v_mul_f32_e32 v125, v211, v125
	v_mul_f32_e32 v126, v212, v126
	v_mul_f32_e32 v127, v213, v127
	v_cvt_pk_bf16_f32 v148, v120, v121
	v_cvt_pk_bf16_f32 v149, v122, v123
	v_cvt_pk_bf16_f32 v150, v124, v125
	v_cvt_pk_bf16_f32 v151, v126, v127
	s_nop 0
	global_store_dwordx4 v2, v[148:151], s[20:21] offset:16
	s_nop 1
	v_mul_f32_e32 v128, v144, v128
	v_mul_f32_e32 v129, v144, v129
	v_mul_f32_e32 v130, v144, v130
	v_mul_f32_e32 v131, v144, v131
	v_mul_f32_e32 v132, v144, v132
	v_mul_f32_e32 v133, v144, v133
	v_mul_f32_e32 v134, v144, v134
	v_mul_f32_e32 v135, v144, v135
	v_mul_f32_e32 v128, v32, v128
	v_mul_f32_e32 v129, v33, v129
	v_mul_f32_e32 v130, v34, v130
	v_mul_f32_e32 v131, v35, v131
	v_mul_f32_e32 v132, v36, v132
	v_mul_f32_e32 v133, v37, v133
	v_mul_f32_e32 v134, v38, v134
	v_mul_f32_e32 v135, v39, v135
	v_mul_f32_e32 v128, v214, v128
	v_mul_f32_e32 v129, v215, v129
	v_mul_f32_e32 v130, v216, v130
	v_mul_f32_e32 v131, v217, v131
	v_mul_f32_e32 v132, v218, v132
	v_mul_f32_e32 v133, v219, v133
	v_mul_f32_e32 v134, v220, v134
	v_mul_f32_e32 v135, v221, v135
	v_cvt_pk_bf16_f32 v148, v128, v129
	v_cvt_pk_bf16_f32 v149, v130, v131
	v_cvt_pk_bf16_f32 v150, v132, v133
	v_cvt_pk_bf16_f32 v151, v134, v135
	s_nop 0
	global_store_dwordx4 v2, v[148:151], s[20:21] offset:32
	s_nop 1
	v_mul_f32_e32 v136, v144, v136
	v_mul_f32_e32 v137, v144, v137
	v_mul_f32_e32 v138, v144, v138
	v_mul_f32_e32 v139, v144, v139
	v_mul_f32_e32 v140, v144, v140
	v_mul_f32_e32 v141, v144, v141
	v_mul_f32_e32 v142, v144, v142
	v_mul_f32_e32 v143, v144, v143
	v_mul_f32_e32 v136, v40, v136
	v_mul_f32_e32 v137, v41, v137
	v_mul_f32_e32 v138, v42, v138
	v_mul_f32_e32 v139, v43, v139
	v_mul_f32_e32 v140, v44, v140
	v_mul_f32_e32 v141, v45, v141
	v_mul_f32_e32 v142, v46, v142
	v_mul_f32_e32 v143, v47, v143
	v_mul_f32_e32 v136, v222, v136
	v_mul_f32_e32 v137, v223, v137
	v_mul_f32_e32 v138, v224, v138
	v_mul_f32_e32 v139, v225, v139
	v_mul_f32_e32 v140, v226, v140
	v_mul_f32_e32 v141, v227, v141
	v_mul_f32_e32 v142, v228, v142
	v_mul_f32_e32 v143, v229, v143
	v_cvt_pk_bf16_f32 v148, v136, v137
	v_cvt_pk_bf16_f32 v149, v138, v139
	v_cvt_pk_bf16_f32 v150, v140, v141
	v_cvt_pk_bf16_f32 v151, v142, v143
	s_nop 0
	global_store_dwordx4 v2, v[148:151], s[20:21] offset:48
	s_nop 1
	s_mov_b32 s8, s22
	s_cmp_lt_u32 s8, 0x4400
	s_cbranch_scc0 .Lg10_done
.Lg10_b:
	s_add_u32 s22, s8, s46
	s_cmp_lt_u32 s22, 0x4400
	s_cbranch_scc0 .Lg10_b_nonext
	s_lshl_b32 s9, s22, 12
	v_add_u32_e32 v4, s9, v2
	s_mul_i32 s9, s22, 0x3000
	v_add_u32_e32 v5, s9, v2
	global_load_dwordx4 v[48:51], v4, s[10:11]
	global_load_dwordx4 v[52:55], v4, s[10:11] offset:16
	global_load_dwordx4 v[56:59], v4, s[10:11] offset:32
	global_load_dwordx4 v[60:63], v4, s[10:11] offset:48
	global_load_dwordx4 v[64:67], v5, s[12:13]
	global_load_dwordx4 v[68:71], v5, s[12:13] offset:16
	global_load_dwordx4 v[72:75], v5, s[12:13] offset:32
	global_load_dwordx4 v[76:79], v5, s[12:13] offset:48
	s_cmp_eq_u32 s23, 0
	s_cbranch_scc1 .Lg10_b_w8
	s_waitcnt vmcnt(12)
	s_branch .Lg10_b_have

; DI float bflo(unsigned u) { return __uint_as_float(u << 16); }
; DI float bfhi(unsigned u) { return __uint_as_float(u & 0xffff0000u); }
; DI void phase_ret_gate(const Params& p) {
;     ...
;     for (int tok = gw; tok < T_TOK; tok += nw) {
;         float o[32]; float ss = 0.f;
; #pragma unroll
;         for (int q = 0; q < 4; ++q) { const u32x4 a = *(const u32x4*)(oraw + (size_t)tok * 2048 + 32 * lane + 8 * q); const unsigned au[4] = {a.x, a.y, a.z, a.w};
; #pragma unroll
;             for (int i = 0; i < 4; ++i) { o[8 * q + 2 * i] = bflo(au[i]); o[8 * q + 2 * i + 1] = bfhi(au[i]); ss += o[8 * q + 2 * i] * o[8 * q + 2 * i] + o[8 * q + 2 * i + 1] * o[8 * q + 2 * i + 1]; } }
;         ss = row16_sum(ss);
;         const float rstd = rsqrtf(ss * (1.f / 512.f) + 1e-6f);
.Lg10_b_have:
	s_mov_b32 s23, 1
	v_lshlrev_b32_e32 v112, 16, v80
	v_and_b32_e32 v113, 0xffff0000, v80
	v_lshlrev_b32_e32 v114, 16, v81
	v_and_b32_e32 v115, 0xffff0000, v81
	v_lshlrev_b32_e32 v116, 16, v82
	v_and_b32_e32 v117, 0xffff0000, v82
	v_lshlrev_b32_e32 v118, 16, v83
	v_and_b32_e32 v119, 0xffff0000, v83
	v_lshlrev_b32_e32 v120, 16, v84
	v_and_b32_e32 v121, 0xffff0000, v84
	v_lshlrev_b32_e32 v122, 16, v85
	v_and_b32_e32 v123, 0xffff0000, v85
	v_lshlrev_b32_e32 v124, 16, v86
	v_and_b32_e32 v125, 0xffff0000, v86
	v_lshlrev_b32_e32 v126, 16, v87
	v_and_b32_e32 v127, 0xffff0000, v87
	v_lshlrev_b32_e32 v128, 16, v88
	v_and_b32_e32 v129, 0xffff0000, v88
	v_lshlrev_b32_e32 v130, 16, v89
	v_and_b32_e32 v131, 0xffff0000, v89
	v_lshlrev_b32_e32 v132, 16, v90
	v_and_b32_e32 v133, 0xffff0000, v90
	v_lshlrev_b32_e32 v134, 16, v91
	v_and_b32_e32 v135, 0xffff0000, v91
	v_lshlrev_b32_e32 v136, 16, v92
	v_and_b32_e32 v137, 0xffff0000, v92
	v_lshlrev_b32_e32 v138, 16, v93
	v_and_b32_e32 v139, 0xffff0000, v93
	v_lshlrev_b32_e32 v140, 16, v94
	v_and_b32_e32 v141, 0xffff0000, v94
	v_lshlrev_b32_e32 v142, 16, v95
	v_and_b32_e32 v143, 0xffff0000, v95
	v_mul_f32_e32 v144, v112, v112
	v_fmac_f32_e32 v144, v113, v113
	v_fmac_f32_e32 v144, v114, v114
	v_fmac_f32_e32 v144, v115, v115
	v_fmac_f32_e32 v144, v116, v116
	v_fmac_f32_e32 v144, v117, v117
	v_fmac_f32_e32 v144, v118, v118
	v_fmac_f32_e32 v144, v119, v119
	v_mul_f32_e32 v145, v120, v120
	v_fmac_f32_e32 v145, v121, v121
	v_fmac_f32_e32 v145, v122, v122
	v_fmac_f32_e32 v145, v123, v123
	v_fmac_f32_e32 v145, v124, v124
	v_fmac_f32_e32 v145, v125, v125
	v_fmac_f32_e32 v145, v126, v126
	v_fmac_f32_e32 v145, v127, v127
	v_mul_f32_e32 v146, v128, v128
	v_fmac_f32_e32 v146, v129, v129
	v_fmac_f32_e32 v146, v130, v130
	v_fmac_f32_e32 v146, v131, v131
	v_fmac_f32_e32 v146, v132, v132
	v_fmac_f32_e32 v146, v133, v133
	v_fmac_f32_e32 v146, v134, v134
	v_fmac_f32_e32 v146, v135, v135
	v_mul_f32_e32 v147, v136, v136
	v_fmac_f32_e32 v147, v137, v137
	v_fmac_f32_e32 v147, v138, v138
	v_fmac_f32_e32 v147, v139, v139
	v_fmac_f32_e32 v147, v140, v140
	v_fmac_f32_e32 v147, v141, v141
	v_fmac_f32_e32 v147, v142, v142
	v_fmac_f32_e32 v147, v143, v143
	v_add_f32_e32 v144, v144, v145
	v_add_f32_e32 v146, v146, v147
	v_add_f32_e32 v144, v144, v146
	v_lshlrev_b32_e32 v198, 16, v96
	v_and_b32_e32 v199, 0xffff0000, v96
	v_lshlrev_b32_e32 v200, 16, v97
	v_and_b32_e32 v201, 0xffff0000, v97
	v_lshlrev_b32_e32 v202, 16, v98
	v_and_b32_e32 v203, 0xffff0000, v98
	v_lshlrev_b32_e32 v204, 16, v99
	v_and_b32_e32 v205, 0xffff0000, v99
	v_lshlrev_b32_e32 v206, 16, v100
	v_and_b32_e32 v207, 0xffff0000, v100
	v_lshlrev_b32_e32 v208, 16, v101
	v_and_b32_e32 v209, 0xffff0000, v101
	v_lshlrev_b32_e32 v210, 16, v102
	v_and_b32_e32 v211, 0xffff0000, v102
	v_lshlrev_b32_e32 v212, 16, v103
	v_and_b32_e32 v213, 0xffff0000, v103
	v_lshlrev_b32_e32 v214, 16, v104
	v_and_b32_e32 v215, 0xffff0000, v104
	v_lshlrev_b32_e32 v216, 16, v105
	v_and_b32_e32 v217, 0xffff0000, v105
	v_lshlrev_b32_e32 v218, 16, v106
	v_and_b32_e32 v219, 0xffff0000, v106
	v_lshlrev_b32_e32 v220, 16, v107
	v_and_b32_e32 v221, 0xffff0000, v107
	v_lshlrev_b32_e32 v222, 16, v108
	v_and_b32_e32 v223, 0xffff0000, v108
	v_lshlrev_b32_e32 v224, 16, v109
	v_and_b32_e32 v225, 0xffff0000, v109
	v_lshlrev_b32_e32 v226, 16, v110
	v_and_b32_e32 v227, 0xffff0000, v110
	v_lshlrev_b32_e32 v228, 16, v111
	v_and_b32_e32 v229, 0xffff0000, v111
	s_nop 1
	v_add_f32_dpp v144, v144, v144 quad_perm:[1,0,3,2] row_mask:0xf bank_mask:0xf bound_ctrl:1
	s_nop 1
	v_add_f32_dpp v144, v144, v144 quad_perm:[2,3,0,1] row_mask:0xf bank_mask:0xf bound_ctrl:1
	s_nop 1
	v_add_f32_dpp v144, v144, v144 row_ror:4 row_mask:0xf bank_mask:0xf bound_ctrl:1
	s_nop 1
	v_add_f32_dpp v144, v144, v144 row_ror:8 row_mask:0xf bank_mask:0xf bound_ctrl:1
	v_fmamk_f32 v144, v144, 0x3b000000, v15
	v_rsq_f32_e32 v144, v144
	v_mul_f32_e32 v148, 0xbfb8aa3b, v198
	v_mul_f32_e32 v149, 0xbfb8aa3b, v199
	v_mul_f32_e32 v150, 0xbfb8aa3b, v200
	v_mul_f32_e32 v151, 0xbfb8aa3b, v201
	v_mul_f32_e32 v152, 0xbfb8aa3b, v202
	v_mul_f32_e32 v153, 0xbfb8aa3b, v203
	v_mul_f32_e32 v154, 0xbfb8aa3b, v204
	v_mul_f32_e32 v155, 0xbfb8aa3b, v205
	v_exp_f32_e32 v148, v148
	v_exp_f32_e32 v149, v149
	v_exp_f32_e32 v150, v150
	v_exp_f32_e32 v151, v151
	v_exp_f32_e32 v152, v152
	v_exp_f32_e32 v153, v153
	v_exp_f32_e32 v154, v154
	v_exp_f32_e32 v155, v155
	v_add_f32_e32 v148, 1.0, v148
	v_add_f32_e32 v149, 1.0, v149
	v_add_f32_e32 v150, 1.0, v150
	v_add_f32_e32 v151, 1.0, v151
	v_add_f32_e32 v152, 1.0, v152
	v_add_f32_e32 v153, 1.0, v153
	v_add_f32_e32 v154, 1.0, v154
	v_add_f32_e32 v155, 1.0, v155
	v_rcp_f32_e32 v148, v148
	v_rcp_f32_e32 v149, v149
	v_rcp_f32_e32 v150, v150
	v_rcp_f32_e32 v151, v151
	v_rcp_f32_e32 v152, v152
	v_rcp_f32_e32 v153, v153
	v_rcp_f32_e32 v154, v154
	v_rcp_f32_e32 v155, v155
	v_mul_f32_e32 v198, v148, v198
	v_mul_f32_e32 v199, v149, v199
	v_mul_f32_e32 v200, v150, v200
	v_mul_f32_e32 v201, v151, v201
	v_mul_f32_e32 v202, v152, v202
	v_mul_f32_e32 v203, v153, v203
	v_mul_f32_e32 v204, v154, v204
	v_mul_f32_e32 v205, v155, v205
	v_mul_f32_e32 v148, 0xbfb8aa3b, v206
	v_mul_f32_e32 v149, 0xbfb8aa3b, v207
	v_mul_f32_e32 v150, 0xbfb8aa3b, v208
	v_mul_f32_e32 v151, 0xbfb8aa3b, v209
	v_mul_f32_e32 v152, 0xbfb8aa3b, v210
	v_mul_f32_e32 v153, 0xbfb8aa3b, v211
	v_mul_f32_e32 v154, 0xbfb8aa3b, v212
	v_mul_f32_e32 v155, 0xbfb8aa3b, v213
	v_exp_f32_e32 v148, v148
	v_exp_f32_e32 v149, v149
	v_exp_f32_e32 v150, v150
	v_exp_f32_e32 v151, v151
	v_exp_f32_e32 v152, v152
	v_exp_f32_e32 v153, v153
	v_exp_f32_e32 v154, v154
	v_exp_f32_e32 v155, v155
; DI unsigned pk_bf16(float a, float b) { f32x2 v = {a, b}; bf2_t r = __builtin_convertvector(v, bf2_t); return __builtin_bit_cast(unsigned, r); }
; DI float bflo(unsigned u) { return __uint_as_float(u << 16); }
; DI float bfhi(unsigned u) { return __uint_as_float(u & 0xffff0000u); }
; DI float silu_f(float x) { return x * __builtin_amdgcn_rcpf(1.f + __expf(-x)); }
; DI void phase_ret_gate(const Params& p) {
;     ...
;         const float* wn = p.onorm_b + 32 * lane;
; #pragma unroll
;         for (int q = 0; q < 4; ++q) { const u32x4 g = *(const u32x4*)(P1 + (size_t)tok * LDP1 + 4096 + 32 * lane + 8 * q); const unsigned gu[4] = {g.x, g.y, g.z, g.w}; unsigned r[4];
; #pragma unroll
;             for (int i = 0; i < 4; ++i) { const float v0 = o[8 * q + 2 * i] * rstd * wn[8 * q + 2 * i] * silu_f(bflo(gu[i])), v1 = o[8 * q + 2 * i + 1] * rstd * wn[8 * q + 2 * i + 1] * silu_f(bfhi(gu[i])); r[i] = pk_bf16(v0, v1); }
;             *(u32x4*)(og + (size_t)tok * 2048 + 32 * lane + 8 * q) = (u32x4){r[0], r[1], r[2], r[3]}; }
	v_add_f32_e32 v148, 1.0, v148
	v_add_f32_e32 v149, 1.0, v149
	v_add_f32_e32 v150, 1.0, v150
	v_add_f32_e32 v151, 1.0, v151
	v_add_f32_e32 v152, 1.0, v152
	v_add_f32_e32 v153, 1.0, v153
	v_add_f32_e32 v154, 1.0, v154
	v_add_f32_e32 v155, 1.0, v155
	v_rcp_f32_e32 v148, v148
	v_rcp_f32_e32 v149, v149
	v_rcp_f32_e32 v150, v150
	v_rcp_f32_e32 v151, v151
	v_rcp_f32_e32 v152, v152
	v_rcp_f32_e32 v153, v153
	v_rcp_f32_e32 v154, v154
	v_rcp_f32_e32 v155, v155
	v_mul_f32_e32 v206, v148, v206
	v_mul_f32_e32 v207, v149, v207
	v_mul_f32_e32 v208, v150, v208
	v_mul_f32_e32 v209, v151, v209
	v_mul_f32_e32 v210, v152, v210
	v_mul_f32_e32 v211, v153, v211
	v_mul_f32_e32 v212, v154, v212
	v_mul_f32_e32 v213, v155, v213
	v_mul_f32_e32 v148, 0xbfb8aa3b, v214
	v_mul_f32_e32 v149, 0xbfb8aa3b, v215
	v_mul_f32_e32 v150, 0xbfb8aa3b, v216
	v_mul_f32_e32 v151, 0xbfb8aa3b, v217
	v_mul_f32_e32 v152, 0xbfb8aa3b, v218
	v_mul_f32_e32 v153, 0xbfb8aa3b, v219
	v_mul_f32_e32 v154, 0xbfb8aa3b, v220
	v_mul_f32_e32 v155, 0xbfb8aa3b, v221
	v_exp_f32_e32 v148, v148
	v_exp_f32_e32 v149, v149
	v_exp_f32_e32 v150, v150
	v_exp_f32_e32 v151, v151
	v_exp_f32_e32 v152, v152
	v_exp_f32_e32 v153, v153
	v_exp_f32_e32 v154, v154
	v_exp_f32_e32 v155, v155
	v_add_f32_e32 v148, 1.0, v148
	v_add_f32_e32 v149, 1.0, v149
	v_add_f32_e32 v150, 1.0, v150
	v_add_f32_e32 v151, 1.0, v151
	v_add_f32_e32 v152, 1.0, v152
	v_add_f32_e32 v153, 1.0, v153
	v_add_f32_e32 v154, 1.0, v154
	v_add_f32_e32 v155, 1.0, v155
	v_rcp_f32_e32 v148, v148
	v_rcp_f32_e32 v149, v149
	v_rcp_f32_e32 v150, v150
	v_rcp_f32_e32 v151, v151
	v_rcp_f32_e32 v152, v152
	v_rcp_f32_e32 v153, v153
	v_rcp_f32_e32 v154, v154
	v_rcp_f32_e32 v155, v155
	v_mul_f32_e32 v214, v148, v214
	v_mul_f32_e32 v215, v149, v215
	v_mul_f32_e32 v216, v150, v216
	v_mul_f32_e32 v217, v151, v217
	v_mul_f32_e32 v218, v152, v218
	v_mul_f32_e32 v219, v153, v219
	v_mul_f32_e32 v220, v154, v220
	v_mul_f32_e32 v221, v155, v221
	v_mul_f32_e32 v148, 0xbfb8aa3b, v222
	v_mul_f32_e32 v149, 0xbfb8aa3b, v223
	v_mul_f32_e32 v150, 0xbfb8aa3b, v224
	v_mul_f32_e32 v151, 0xbfb8aa3b, v225
	v_mul_f32_e32 v152, 0xbfb8aa3b, v226
	v_mul_f32_e32 v153, 0xbfb8aa3b, v227
	v_mul_f32_e32 v154, 0xbfb8aa3b, v228
	v_mul_f32_e32 v155, 0xbfb8aa3b, v229
	v_exp_f32_e32 v148, v148
	v_exp_f32_e32 v149, v149
	v_exp_f32_e32 v150, v150
	v_exp_f32_e32 v151, v151
	v_exp_f32_e32 v152, v152
	v_exp_f32_e32 v153, v153
	v_exp_f32_e32 v154, v154
	v_exp_f32_e32 v155, v155
	v_add_f32_e32 v148, 1.0, v148
	v_add_f32_e32 v149, 1.0, v149
	v_add_f32_e32 v150, 1.0, v150
	v_add_f32_e32 v151, 1.0, v151
	v_add_f32_e32 v152, 1.0, v152
	v_add_f32_e32 v153, 1.0, v153
	v_add_f32_e32 v154, 1.0, v154
	v_add_f32_e32 v155, 1.0, v155
	v_rcp_f32_e32 v148, v148
	v_rcp_f32_e32 v149, v149
	v_rcp_f32_e32 v150, v150
	v_rcp_f32_e32 v151, v151
	v_rcp_f32_e32 v152, v152
	v_rcp_f32_e32 v153, v153
	v_rcp_f32_e32 v154, v154
	v_rcp_f32_e32 v155, v155
	v_mul_f32_e32 v222, v148, v222
	v_mul_f32_e32 v223, v149, v223
	v_mul_f32_e32 v224, v150, v224
	v_mul_f32_e32 v225, v151, v225
	v_mul_f32_e32 v226, v152, v226
	v_mul_f32_e32 v227, v153, v227
	v_mul_f32_e32 v228, v154, v228
	v_mul_f32_e32 v229, v155, v229
	s_lshl_b32 s9, s8, 12
	s_add_u32 s20, s16, s9
	s_addc_u32 s21, s17, 0
	v_mul_f32_e32 v112, v144, v112
	v_mul_f32_e32 v113, v144, v113
	v_mul_f32_e32 v114, v144, v114
	v_mul_f32_e32 v115, v144, v115
	v_mul_f32_e32 v116, v144, v116
	v_mul_f32_e32 v117, v144, v117
	v_mul_f32_e32 v118, v144, v118
	v_mul_f32_e32 v119, v144, v119
	v_mul_f32_e32 v112, v16, v112
	v_mul_f32_e32 v113, v17, v113
	v_mul_f32_e32 v114, v18, v114
	v_mul_f32_e32 v115, v19, v115
	v_mul_f32_e32 v116, v20, v116
	v_mul_f32_e32 v117, v21, v117
	v_mul_f32_e32 v118, v22, v118
	v_mul_f32_e32 v119, v23, v119
	v_mul_f32_e32 v112, v198, v112
	v_mul_f32_e32 v113, v199, v113
	v_mul_f32_e32 v114, v200, v114
	v_mul_f32_e32 v115, v201, v115
	v_mul_f32_e32 v116, v202, v116
	v_mul_f32_e32 v117, v203, v117
	v_mul_f32_e32 v118, v204, v118
	v_mul_f32_e32 v119, v205, v119
	v_cvt_pk_bf16_f32 v148, v112, v113
	v_cvt_pk_bf16_f32 v149, v114, v115
	v_cvt_pk_bf16_f32 v150, v116, v117
; DI unsigned pk_bf16(float a, float b) { f32x2 v = {a, b}; bf2_t r = __builtin_convertvector(v, bf2_t); return __builtin_bit_cast(unsigned, r); }
; DI float bflo(unsigned u) { return __uint_as_float(u << 16); }
; DI float bfhi(unsigned u) { return __uint_as_float(u & 0xffff0000u); }
; DI float silu_f(float x) { return x * __builtin_amdgcn_rcpf(1.f + __expf(-x)); }
; DI void phase_ret_gate(const Params& p) {
;     ...
;         for (int q = 0; q < 4; ++q) { const u32x4 g = *(const u32x4*)(P1 + (size_t)tok * LDP1 + 4096 + 32 * lane + 8 * q); const unsigned gu[4] = {g.x, g.y, g.z, g.w}; unsigned r[4];
; #pragma unroll
;             for (int i = 0; i < 4; ++i) { const float v0 = o[8 * q + 2 * i] * rstd * wn[8 * q + 2 * i] * silu_f(bflo(gu[i])), v1 = o[8 * q + 2 * i + 1] * rstd * wn[8 * q + 2 * i + 1] * silu_f(bfhi(gu[i])); r[i] = pk_bf16(v0, v1); }
;             *(u32x4*)(og + (size_t)tok * 2048 + 32 * lane + 8 * q) = (u32x4){r[0], r[1], r[2], r[3]}; }
;     }
	v_cvt_pk_bf16_f32 v151, v118, v119
	s_nop 0
	global_store_dwordx4 v2, v[148:151], s[20:21]
	s_nop 1
	v_mul_f32_e32 v120, v144, v120
	v_mul_f32_e32 v121, v144, v121
	v_mul_f32_e32 v122, v144, v122
	v_mul_f32_e32 v123, v144, v123
	v_mul_f32_e32 v124, v144, v124
	v_mul_f32_e32 v125, v144, v125
	v_mul_f32_e32 v126, v144, v126
	v_mul_f32_e32 v127, v144, v127
	v_mul_f32_e32 v120, v24, v120
	v_mul_f32_e32 v121, v25, v121
	v_mul_f32_e32 v122, v26, v122
	v_mul_f32_e32 v123, v27, v123
	v_mul_f32_e32 v124, v28, v124
	v_mul_f32_e32 v125, v29, v125
	v_mul_f32_e32 v126, v30, v126
	v_mul_f32_e32 v127, v31, v127
	v_mul_f32_e32 v120, v206, v120
	v_mul_f32_e32 v121, v207, v121
	v_mul_f32_e32 v122, v208, v122
	v_mul_f32_e32 v123, v209, v123
	v_mul_f32_e32 v124, v210, v124
	v_mul_f32_e32 v125, v211, v125
	v_mul_f32_e32 v126, v212, v126
	v_mul_f32_e32 v127, v213, v127
	v_cvt_pk_bf16_f32 v148, v120, v121
	v_cvt_pk_bf16_f32 v149, v122, v123
	v_cvt_pk_bf16_f32 v150, v124, v125
	v_cvt_pk_bf16_f32 v151, v126, v127
	s_nop 0
	global_store_dwordx4 v2, v[148:151], s[20:21] offset:16
	s_nop 1
	v_mul_f32_e32 v128, v144, v128
	v_mul_f32_e32 v129, v144, v129
	v_mul_f32_e32 v130, v144, v130
	v_mul_f32_e32 v131, v144, v131
	v_mul_f32_e32 v132, v144, v132
	v_mul_f32_e32 v133, v144, v133
	v_mul_f32_e32 v134, v144, v134
	v_mul_f32_e32 v135, v144, v135
	v_mul_f32_e32 v128, v32, v128
	v_mul_f32_e32 v129, v33, v129
	v_mul_f32_e32 v130, v34, v130
	v_mul_f32_e32 v131, v35, v131
	v_mul_f32_e32 v132, v36, v132
	v_mul_f32_e32 v133, v37, v133
	v_mul_f32_e32 v134, v38, v134
	v_mul_f32_e32 v135, v39, v135
	v_mul_f32_e32 v128, v214, v128
	v_mul_f32_e32 v129, v215, v129
	v_mul_f32_e32 v130, v216, v130
	v_mul_f32_e32 v131, v217, v131
	v_mul_f32_e32 v132, v218, v132
	v_mul_f32_e32 v133, v219, v133
	v_mul_f32_e32 v134, v220, v134
	v_mul_f32_e32 v135, v221, v135
	v_cvt_pk_bf16_f32 v148, v128, v129
	v_cvt_pk_bf16_f32 v149, v130, v131
	v_cvt_pk_bf16_f32 v150, v132, v133
	v_cvt_pk_bf16_f32 v151, v134, v135
	s_nop 0
	global_store_dwordx4 v2, v[148:151], s[20:21] offset:32
	s_nop 1
	v_mul_f32_e32 v136, v144, v136
	v_mul_f32_e32 v137, v144, v137
	v_mul_f32_e32 v138, v144, v138
	v_mul_f32_e32 v139, v144, v139
	v_mul_f32_e32 v140, v144, v140
	v_mul_f32_e32 v141, v144, v141
	v_mul_f32_e32 v142, v144, v142
	v_mul_f32_e32 v143, v144, v143
	v_mul_f32_e32 v136, v40, v136
	v_mul_f32_e32 v137, v41, v137
	v_mul_f32_e32 v138, v42, v138
	v_mul_f32_e32 v139, v43, v139
	v_mul_f32_e32 v140, v44, v140
	v_mul_f32_e32 v141, v45, v141
	v_mul_f32_e32 v142, v46, v142
	v_mul_f32_e32 v143, v47, v143
	v_mul_f32_e32 v136, v222, v136
	v_mul_f32_e32 v137, v223, v137
	v_mul_f32_e32 v138, v224, v138
	v_mul_f32_e32 v139, v225, v139
	v_mul_f32_e32 v140, v226, v140
	v_mul_f32_e32 v141, v227, v141
	v_mul_f32_e32 v142, v228, v142
	v_mul_f32_e32 v143, v229, v143
	v_cvt_pk_bf16_f32 v148, v136, v137
	v_cvt_pk_bf16_f32 v149, v138, v139
	v_cvt_pk_bf16_f32 v150, v140, v141
	v_cvt_pk_bf16_f32 v151, v142, v143
	s_nop 0
	global_store_dwordx4 v2, v[148:151], s[20:21] offset:48
	s_nop 1
	s_mov_b32 s8, s22
	s_cmp_lt_u32 s8, 0x4400
	s_cbranch_scc1 .Lg10_a
.Lg10_done:
.LBB0_1449:
	s_or_b64 exec, exec, s[6:7]
	s_cmp_gt_i32 s81, 11
	s_cselect_b64 s[0:1], -1, 0
	s_and_b64 s[4:5], s[4:5], s[0:1]
	s_andn2_b64 vcc, exec, s[4:5]
	s_cbranch_vccnz .LBB0_1517
	s_cmp_eq_u32 s82, 0
	s_cbranch_scc1 .LBB0_1462
	v_lshrrev_b32_e32 v2, 20, v0
	v_lshrrev_b32_e32 v3, 10, v0
	v_or_b32_e32 v2, v3, v2
	s_movk_i32 s3, 0x3ff
	v_and_or_b32 v2, v2, s3, v1
	v_cmp_eq_u32_e32 vcc, 0, v2
	s_waitcnt vmcnt(0) lgkmcnt(0)
	s_barrier
	s_and_saveexec_b64 s[4:5], vcc
	s_cbranch_execz .LBB0_1461
	v_readlane_b32 s6, v238, 0
	v_readlane_b32 s7, v238, 1
	buffer_wbl2 sc1
	s_load_dwordx2 s[6:7], s[6:7], 0x58
	v_mov_b32_e32 v4, 0
	s_mov_b64 s[8:9], exec
	v_mbcnt_lo_u32_b32 v3, s8, 0
	v_mbcnt_hi_u32_b32 v3, s9, v3
	s_waitcnt lgkmcnt(0)
	global_load_dword v2, v4, s[6:7] offset:40
	v_cmp_eq_u32_e32 vcc, 0, v3
	s_and_saveexec_b64 s[10:11], vcc
	s_cbranch_execz .LBB0_1454
	s_bcnt1_i32_b64 s3, s[8:9]
	v_mov_b32_e32 v5, s3
	global_atomic_add v5, v4, v5, s[6:7] offset:32 sc0
